# attention softmax: lane-half exchange of the row maximum moved into the rare re-reference path (the growth test is per lane), max tree one op shorter
# speedup vs baseline: 1.0032x; 1.0032x over previous
; #define AT_GLOADK(k0) do { kreg = *(const u32x4*)(Kb + (size_t)((k0) + (tid >> 3)) * 64 + (tid & 7) * 8); \
;             if (MLA) preg = *(const u32x2*)(Pb + (size_t)((k0) + (tid >> 3)) * 32 + (tid & 7) * 4); } while (0)
; #define AT_GLOADV(k0) do { vreg = *(const u32x4*)(Vb + (size_t)((k0) + (tid >> 3)) * 64 + (tid & 7) * 8); } while (0)
; #define AT_WRITEK(buf) do { *(LAS u32x4*)(lds + (buf) * KBUF + (tid >> 3) * KSTR + (tid & 7) * 16) = kreg; \
;             if (MLA) *(LAS u32x2*)(lds + (buf) * KBUF + (tid >> 3) * KSTR + 128 + (tid & 7) * 8) = preg; } while (0)
; #define AT_WRITEV(buf) do { *(LAS u32x4*)(lds + 2 * KBUF + (buf) * VBUF + (tid >> 3) * VSTR + (tid & 7) * 16) = vreg; } while (0)
; template <bool MLA>
; DI void attn_phase(const int TID, const int BID, LAS unsigned char* lds, const Params& p, bool need_ctx) {
;     ...
;         AT_GLOADK(0); AT_GLOADV(0); AT_WRITEK(0); AT_WRITEV(0);
;         AT_GLOADK(64); AT_WRITEK(1);
;         __syncthreads();
;         AT_QK(sa0, sa1, 0);
;         __syncthreads();
.Lamla_prio:
	ds_read_b128 v[136:139], v243 offset:0
	ds_read_b128 v[140:143], v243 offset:6656
	ds_read_b128 v[144:147], v243 offset:32
	ds_read_b128 v[148:151], v243 offset:6688
	s_waitcnt lgkmcnt(3)
	v_mfma_f32_32x32x16_bf16 v[32:47], v[136:139], v[112:115], 0
	ds_read_b128 v[136:139], v243 offset:64
	s_waitcnt lgkmcnt(3)
	v_mfma_f32_32x32x16_bf16 v[48:63], v[140:143], v[112:115], 0
	ds_read_b128 v[140:143], v243 offset:6720
	s_waitcnt lgkmcnt(3)
	v_mfma_f32_32x32x16_bf16 v[32:47], v[144:147], v[116:119], v[32:47]
	ds_read_b128 v[144:147], v243 offset:96
	s_waitcnt lgkmcnt(3)
	v_mfma_f32_32x32x16_bf16 v[48:63], v[148:151], v[116:119], v[48:63]
	ds_read_b128 v[148:151], v243 offset:6752
	s_waitcnt lgkmcnt(3)
	v_mfma_f32_32x32x16_bf16 v[32:47], v[136:139], v[120:123], v[32:47]
	ds_read_b128 v[136:139], v243 offset:128
	s_waitcnt lgkmcnt(3)
	v_mfma_f32_32x32x16_bf16 v[48:63], v[140:143], v[120:123], v[48:63]
	ds_read_b128 v[140:143], v243 offset:6784
	s_waitcnt lgkmcnt(3)
	v_mfma_f32_32x32x16_bf16 v[32:47], v[144:147], v[124:127], v[32:47]
	ds_read_b128 v[144:147], v243 offset:160
	s_waitcnt lgkmcnt(3)
	v_mfma_f32_32x32x16_bf16 v[48:63], v[148:151], v[124:127], v[48:63]
	ds_read_b128 v[148:151], v243 offset:6816
	s_waitcnt lgkmcnt(3)
	v_mfma_f32_32x32x16_bf16 v[32:47], v[136:139], v[128:131], v[32:47]
	s_waitcnt lgkmcnt(2)
	v_mfma_f32_32x32x16_bf16 v[48:63], v[140:143], v[128:131], v[48:63]
	s_waitcnt lgkmcnt(1)
	v_mfma_f32_32x32x16_bf16 v[32:47], v[144:147], v[132:135], v[32:47]
	s_waitcnt lgkmcnt(0)
	v_mfma_f32_32x32x16_bf16 v[48:63], v[148:151], v[132:135], v[48:63]
	s_waitcnt lgkmcnt(0)
	s_nop 7
	s_barrier
	ds_read_b128 v[136:139], v243 offset:13312
	ds_read_b128 v[140:143], v243 offset:19968
	ds_read_b128 v[144:147], v243 offset:13344
	ds_read_b128 v[148:151], v243 offset:20000
	v_max3_f32 v168, v32, v33, v34
	v_max3_f32 v170, v48, v49, v50
	v_max3_f32 v168, v168, v35, v36
	v_max3_f32 v170, v170, v51, v52
	v_max3_f32 v168, v168, v37, v38
	v_max3_f32 v170, v170, v53, v54
	v_max3_f32 v168, v168, v39, v40
	v_max3_f32 v170, v170, v55, v56
	v_max3_f32 v168, v168, v41, v42
	v_max3_f32 v170, v170, v57, v58
	v_max3_f32 v168, v168, v43, v44
	v_max3_f32 v170, v170, v59, v60
	v_max3_f32 v168, v168, v45, v46
	v_max3_f32 v170, v170, v61, v62
	v_max3_f32 v168, v168, v170, v47
	v_max_f32_e32 v168, v168, v63
	v_mov_b32_e32 v170, v168
	s_nop 1
	v_permlane32_swap_b32_e32 v168, v170
	v_max_f32_e32 v168, v168, v170
	v_mov_b32_e32 v170, v168
	v_sub_f32_e32 v218, v218, v170
	v_sub_f32_e32 v219, v219, v170
	v_sub_f32_e32 v220, v220, v170
	v_sub_f32_e32 v221, v221, v170
	v_sub_f32_e32 v222, v222, v170
	v_sub_f32_e32 v223, v223, v170
	v_sub_f32_e32 v224, v224, v170
	v_sub_f32_e32 v225, v225, v170
	v_sub_f32_e32 v226, v226, v170
	v_sub_f32_e32 v227, v227, v170
	v_sub_f32_e32 v228, v228, v170
	v_sub_f32_e32 v229, v229, v170
	v_sub_f32_e32 v230, v230, v170
	v_sub_f32_e32 v231, v231, v170
	v_sub_f32_e32 v232, v232, v170
	v_sub_f32_e32 v233, v233, v170
	v_sub_f32_e32 v32, v32, v170
	v_sub_f32_e32 v33, v33, v170
	v_sub_f32_e32 v34, v34, v170
	v_sub_f32_e32 v35, v35, v170
	v_sub_f32_e32 v36, v36, v170
	v_sub_f32_e32 v37, v37, v170
	v_sub_f32_e32 v38, v38, v170
	v_sub_f32_e32 v39, v39, v170
	v_sub_f32_e32 v40, v40, v170
	v_sub_f32_e32 v41, v41, v170
	v_sub_f32_e32 v42, v42, v170
	v_sub_f32_e32 v43, v43, v170
	v_sub_f32_e32 v44, v44, v170
	v_sub_f32_e32 v45, v45, v170
	v_sub_f32_e32 v46, v46, v170
	v_sub_f32_e32 v47, v47, v170
	v_sub_f32_e32 v48, v48, v170
	v_sub_f32_e32 v49, v49, v170
	v_sub_f32_e32 v50, v50, v170
	v_sub_f32_e32 v51, v51, v170
	v_sub_f32_e32 v52, v52, v170
	v_sub_f32_e32 v53, v53, v170
	v_sub_f32_e32 v54, v54, v170
	v_sub_f32_e32 v55, v55, v170
	v_sub_f32_e32 v56, v56, v170
	v_sub_f32_e32 v57, v57, v170
	v_sub_f32_e32 v58, v58, v170
	v_sub_f32_e32 v59, v59, v170
	v_sub_f32_e32 v60, v60, v170
	v_sub_f32_e32 v61, v61, v170
	v_sub_f32_e32 v62, v62, v170
	v_sub_f32_e32 v63, v63, v170
	s_waitcnt lgkmcnt(3)
	v_mfma_f32_32x32x16_bf16 v[64:79], v[136:139], v[112:115], v[218:233]
	v_exp_f32_e32 v32, v32
	v_exp_f32_e32 v48, v48
	v_exp_f32_e32 v33, v33
	v_exp_f32_e32 v49, v49
	v_exp_f32_e32 v34, v34
	ds_read_b128 v[136:139], v243 offset:13376
	s_mov_b32 s55, s52
	s_mov_b32 s52, s53
	s_mov_b32 s53, s54
	s_mov_b32 s54, s55
	s_mov_b32 s9, 0
	s_waitcnt lgkmcnt(3)
	v_mfma_f32_32x32x16_bf16 v[80:95], v[140:143], v[112:115], v[218:233]
	v_exp_f32_e32 v50, v50
	v_cvt_pk_bf16_f32 v96, v32, v33
	v_cvt_pk_bf16_f32 v104, v48, v49
	v_exp_f32_e32 v35, v35
	v_exp_f32_e32 v51, v51
	ds_read_b128 v[140:143], v243 offset:20032
	global_load_dwordx4 v[208:211], v167, s[2:3]
	global_load_dwordx2 v[216:217], v165, s[10:11]
	global_load_dwordx4 v[212:215], v167, s[4:5]
	s_add_u32 s2, s2, 0x2000
	s_addc_u32 s3, s3, 0
	s_add_u32 s10, s10, 0x1000
	s_addc_u32 s11, s11, 0
	s_add_u32 s4, s4, 0x2000
	s_addc_u32 s5, s5, 0
	v_add_u32_e32 v163, s53, v240
	v_add_u32_e32 v164, s54, v241
	s_waitcnt lgkmcnt(3)
	v_mfma_f32_32x32x16_bf16 v[64:79], v[144:147], v[116:119], v[64:79]
	v_exp_f32_e32 v36, v36
	v_exp_f32_e32 v52, v52
	v_cvt_pk_bf16_f32 v97, v34, v35
	v_cvt_pk_bf16_f32 v105, v50, v51
	v_exp_f32_e32 v37, v37
	ds_read_b128 v[144:147], v243 offset:13408
	s_waitcnt lgkmcnt(3)
	v_mfma_f32_32x32x16_bf16 v[80:95], v[148:151], v[116:119], v[80:95]
	v_exp_f32_e32 v53, v53
	v_exp_f32_e32 v38, v38
	v_exp_f32_e32 v54, v54
	v_cvt_pk_bf16_f32 v98, v36, v37
	ds_read_b128 v[148:151], v243 offset:20064
	s_waitcnt lgkmcnt(3)
	v_mfma_f32_32x32x16_bf16 v[64:79], v[136:139], v[120:123], v[64:79]
	v_cvt_pk_bf16_f32 v106, v52, v53
	v_exp_f32_e32 v39, v39
	v_exp_f32_e32 v55, v55
	v_exp_f32_e32 v40, v40
	v_exp_f32_e32 v56, v56
	ds_read_b128 v[136:139], v243 offset:13440
	s_waitcnt lgkmcnt(3)
	v_mfma_f32_32x32x16_bf16 v[80:95], v[140:143], v[120:123], v[80:95]
	v_cvt_pk_bf16_f32 v99, v38, v39
	v_cvt_pk_bf16_f32 v107, v54, v55
	v_exp_f32_e32 v41, v41
	v_exp_f32_e32 v57, v57
	v_exp_f32_e32 v42, v42
	ds_read_b128 v[140:143], v243 offset:20096
	s_waitcnt lgkmcnt(3)
	v_mfma_f32_32x32x16_bf16 v[64:79], v[144:147], v[124:127], v[64:79]
	v_exp_f32_e32 v58, v58
	v_cvt_pk_bf16_f32 v100, v40, v41
	v_cvt_pk_bf16_f32 v108, v56, v57
	v_exp_f32_e32 v43, v43
	v_exp_f32_e32 v59, v59
	ds_read_b128 v[144:147], v243 offset:13472
	ds_read_b64_tr_b16 v[176:177], v163 offset:0
	ds_read_b64_tr_b16 v[178:179], v163 offset:1536
	s_waitcnt vmcnt(5)
	ds_write_b128 v238, v[152:155]
	s_waitcnt vmcnt(4)
	ds_write_b64 v239, v[160:161]
	s_waitcnt vmcnt(3)
	ds_write_b128 v164, v[156:159]
	s_waitcnt lgkmcnt(8)
	v_mfma_f32_32x32x16_bf16 v[80:95], v[148:151], v[124:127], v[80:95]
	v_exp_f32_e32 v44, v44
	v_exp_f32_e32 v60, v60
	v_cvt_pk_bf16_f32 v101, v42, v43
	v_cvt_pk_bf16_f32 v109, v58, v59
	v_exp_f32_e32 v45, v45
	ds_read_b128 v[148:151], v243 offset:20128
	ds_read_b64_tr_b16 v[180:181], v163 offset:64
	ds_read_b64_tr_b16 v[182:183], v163 offset:1600
	s_waitcnt lgkmcnt(10)
	v_mfma_f32_32x32x16_bf16 v[64:79], v[136:139], v[128:131], v[64:79]
	v_exp_f32_e32 v61, v61
	v_exp_f32_e32 v46, v46
	v_exp_f32_e32 v62, v62
	v_cvt_pk_bf16_f32 v102, v44, v45
	v_cvt_pk_bf16_f32 v110, v60, v61
	ds_read_b64_tr_b16 v[184:185], v163 offset:6144
	ds_read_b64_tr_b16 v[186:187], v163 offset:7680
	s_waitcnt lgkmcnt(11)
	v_mfma_f32_32x32x16_bf16 v[80:95], v[140:143], v[128:131], v[80:95]
	v_exp_f32_e32 v47, v47
	v_exp_f32_e32 v63, v63
	v_cvt_pk_bf16_f32 v103, v46, v47
	v_cvt_pk_bf16_f32 v111, v62, v63
	ds_read_b64_tr_b16 v[188:189], v163 offset:6208
	ds_read_b64_tr_b16 v[190:191], v163 offset:7744
	s_waitcnt lgkmcnt(12)
	v_mfma_f32_32x32x16_bf16 v[64:79], v[144:147], v[132:135], v[64:79]
	s_waitcnt lgkmcnt(6)
	v_mfma_f32_32x32x16_bf16 v[80:95], v[148:151], v[132:135], v[80:95]
	s_nop 13
	s_waitcnt lgkmcnt(0)
	s_barrier
	s_cmp_eq_u32 s7, 0
	s_cbranch_scc1 .Lamla_tail
.Lamla_loop:
	ds_read_b128 v[136:139], v243 offset:0
	ds_read_b128 v[140:143], v243 offset:6656
	ds_read_b128 v[144:147], v243 offset:32
	ds_read_b128 v[148:151], v243 offset:6688
	s_waitcnt lgkmcnt(10)
	v_mfma_f32_32x32x16_bf16 v[0:15], v[176:179], v[96:99], v[0:15]
	v_max3_f32 v168, v64, v65, v66
	v_max3_f32 v170, v80, v81, v82
	v_max3_f32 v168, v168, v67, v68
	v_max3_f32 v170, v170, v83, v84
	v_max3_f32 v168, v168, v69, v70
	s_mov_b32 s55, s52
	s_mov_b32 s52, s53
	s_mov_b32 s53, s54
	s_mov_b32 s54, s55
	s_mov_b32 s9, 0
	s_waitcnt lgkmcnt(8)
	v_mfma_f32_32x32x16_bf16 v[16:31], v[180:183], v[96:99], v[16:31]
	v_max3_f32 v170, v170, v85, v86
	v_max3_f32 v168, v168, v71, v72
	v_max3_f32 v170, v170, v87, v88
	v_max3_f32 v168, v168, v73, v74
	global_load_dwordx4 v[152:155], v167, s[2:3]
	global_load_dwordx2 v[160:161], v165, s[10:11]
	global_load_dwordx4 v[156:159], v167, s[4:5]
	s_add_u32 s2, s2, 0x2000
	s_addc_u32 s3, s3, 0
	s_add_u32 s10, s10, 0x1000
	s_addc_u32 s11, s11, 0
	s_add_u32 s4, s4, 0x2000
	s_addc_u32 s5, s5, 0
	v_add_u32_e32 v162, s53, v240
	v_add_u32_e32 v164, s54, v241
	v_mfma_f32_16x16x32_bf16 v[234:237], v[246:249], v[96:99], v[234:237]
	v_max3_f32 v170, v170, v89, v90
	v_max3_f32 v168, v168, v75, v76
	v_max3_f32 v170, v170, v91, v92
	v_max3_f32 v168, v168, v77, v78
	v_max3_f32 v170, v170, v93, v94
	v_max3_f32 v168, v168, v170, v79
	v_max_f32_e32 v168, v168, v95
	v_cmp_lt_f32_e32 vcc, 0x41000000, v168
	s_cbranch_vccz .Lamla_nors_2
	v_mov_b32_e32 v170, v168
	s_nop 1
	v_permlane32_swap_b32_e32 v168, v170
	v_max_f32_e32 v168, v168, v170
	v_max_f32_e32 v170, 0, v168
	v_exp_f32_e64 v166, -v170
	v_sub_f32_e32 v218, v218, v170
	v_sub_f32_e32 v219, v219, v170
	v_sub_f32_e32 v220, v220, v170
	v_sub_f32_e32 v221, v221, v170
	v_sub_f32_e32 v222, v222, v170
	v_sub_f32_e32 v223, v223, v170
	v_sub_f32_e32 v224, v224, v170
	v_sub_f32_e32 v225, v225, v170
	v_sub_f32_e32 v226, v226, v170
	v_sub_f32_e32 v227, v227, v170
	v_sub_f32_e32 v228, v228, v170
	v_sub_f32_e32 v229, v229, v170
	v_sub_f32_e32 v230, v230, v170
	v_sub_f32_e32 v231, v231, v170
	v_sub_f32_e32 v232, v232, v170
	v_sub_f32_e32 v233, v233, v170
	v_sub_f32_e32 v64, v64, v170
	v_sub_f32_e32 v65, v65, v170
	v_sub_f32_e32 v66, v66, v170
	v_sub_f32_e32 v67, v67, v170
	v_sub_f32_e32 v68, v68, v170
	v_sub_f32_e32 v69, v69, v170
	v_sub_f32_e32 v70, v70, v170
	v_sub_f32_e32 v71, v71, v170
	v_sub_f32_e32 v72, v72, v170
	v_sub_f32_e32 v73, v73, v170
	v_sub_f32_e32 v74, v74, v170
	v_sub_f32_e32 v75, v75, v170
	v_sub_f32_e32 v76, v76, v170
	v_sub_f32_e32 v77, v77, v170
	v_sub_f32_e32 v78, v78, v170
	v_sub_f32_e32 v79, v79, v170
	v_sub_f32_e32 v80, v80, v170
	v_sub_f32_e32 v81, v81, v170
	v_sub_f32_e32 v82, v82, v170
	v_sub_f32_e32 v83, v83, v170
	v_sub_f32_e32 v84, v84, v170
	v_sub_f32_e32 v85, v85, v170
	v_sub_f32_e32 v86, v86, v170
	v_sub_f32_e32 v87, v87, v170
	v_sub_f32_e32 v88, v88, v170
	v_sub_f32_e32 v89, v89, v170
	v_sub_f32_e32 v90, v90, v170
	v_sub_f32_e32 v91, v91, v170
	v_sub_f32_e32 v92, v92, v170
	v_sub_f32_e32 v93, v93, v170
	v_sub_f32_e32 v94, v94, v170
	v_sub_f32_e32 v95, v95, v170
	s_mov_b32 s9, 1
.Lamla_nors_2:
	s_waitcnt lgkmcnt(3)
	v_mfma_f32_32x32x16_bf16 v[32:47], v[136:139], v[112:115], v[218:233]
	v_exp_f32_e32 v64, v64
	v_exp_f32_e32 v80, v80
	ds_read_b128 v[136:139], v243 offset:64
	ds_read_b64_tr_b16 v[192:193], v163 offset:3072
	ds_read_b64_tr_b16 v[194:195], v163 offset:4608
	s_waitcnt lgkmcnt(5)
	v_mfma_f32_32x32x16_bf16 v[48:63], v[140:143], v[112:115], v[218:233]
	v_exp_f32_e32 v65, v65
	v_exp_f32_e32 v81, v81
	ds_read_b128 v[140:143], v243 offset:6720
	ds_read_b64_tr_b16 v[196:197], v163 offset:3136
	ds_read_b64_tr_b16 v[198:199], v163 offset:4672
	v_mfma_f32_32x32x16_bf16 v[0:15], v[184:187], v[104:107], v[0:15]
	v_exp_f32_e32 v66, v66
	v_exp_f32_e32 v82, v82
	ds_read_b64_tr_b16 v[200:201], v163 offset:9216
	ds_read_b64_tr_b16 v[202:203], v163 offset:10752
	s_waitcnt lgkmcnt(9)
	v_mfma_f32_32x32x16_bf16 v[32:47], v[144:147], v[116:119], v[32:47]
	v_cvt_pk_bf16_f32 v96, v64, v65
	v_exp_f32_e32 v67, v67
	v_exp_f32_e32 v83, v83
	ds_read_b128 v[144:147], v243 offset:96
	ds_read_b64_tr_b16 v[204:205], v163 offset:9280
	ds_read_b64_tr_b16 v[206:207], v163 offset:10816
	v_mfma_f32_32x32x16_bf16 v[16:31], v[188:191], v[104:107], v[16:31]
	v_exp_f32_e32 v68, v68
	v_exp_f32_e32 v84, v84
	s_waitcnt lgkmcnt(11)
	v_mfma_f32_32x32x16_bf16 v[48:63], v[148:151], v[116:119], v[48:63]
	v_cvt_pk_bf16_f32 v97, v66, v67
	v_exp_f32_e32 v69, v69
	ds_read_b128 v[148:151], v243 offset:6752
	v_mfma_f32_16x16x32_bf16 v[234:237], v[246:249], v[104:107], v[234:237]
	v_cvt_pk_bf16_f32 v104, v80, v81
	v_cvt_pk_bf16_f32 v105, v82, v83
	v_exp_f32_e32 v85, v85
	v_exp_f32_e32 v70, v70
	s_waitcnt lgkmcnt(11)
	v_mfma_f32_32x32x16_bf16 v[32:47], v[136:139], v[120:123], v[32:47]
	v_exp_f32_e32 v86, v86
	v_cvt_pk_bf16_f32 v98, v68, v69
	v_cvt_pk_bf16_f32 v106, v84, v85
	ds_read_b128 v[136:139], v243 offset:128
	s_waitcnt lgkmcnt(9)
	v_mfma_f32_32x32x16_bf16 v[48:63], v[140:143], v[120:123], v[48:63]
	v_exp_f32_e32 v71, v71
	v_exp_f32_e32 v87, v87
	ds_read_b128 v[140:143], v243 offset:6784
	v_mfma_f32_32x32x16_bf16 v[0:15], v[192:195], v[100:103], v[0:15]
	v_exp_f32_e32 v72, v72
	v_exp_f32_e32 v88, v88
	v_cvt_pk_bf16_f32 v99, v70, v71
	s_waitcnt lgkmcnt(5)
	v_mfma_f32_32x32x16_bf16 v[32:47], v[144:147], v[124:127], v[32:47]
	v_cvt_pk_bf16_f32 v107, v86, v87
	v_exp_f32_e32 v73, v73
	v_exp_f32_e32 v89, v89
	ds_read_b128 v[144:147], v243 offset:160
	v_mfma_f32_32x32x16_bf16 v[16:31], v[196:199], v[100:103], v[16:31]
	v_exp_f32_e32 v74, v74
	v_exp_f32_e32 v90, v90
	s_waitcnt vmcnt(5)
	ds_write_b128 v238, v[208:211] offset:13312
	s_waitcnt vmcnt(4)
	ds_write_b64 v239, v[216:217] offset:13312
	s_waitcnt vmcnt(3)
	ds_write_b128 v164, v[212:215]
	s_waitcnt lgkmcnt(6)
	v_mfma_f32_32x32x16_bf16 v[48:63], v[148:151], v[124:127], v[48:63]
	v_exp_f32_e32 v75, v75
	v_exp_f32_e32 v91, v91
	ds_read_b128 v[148:151], v243 offset:6816
	v_mfma_f32_16x16x32_bf16 v[234:237], v[246:249], v[100:103], v[234:237]
	v_cvt_pk_bf16_f32 v100, v72, v73
	v_exp_f32_e32 v76, v76
	v_exp_f32_e32 v92, v92
	s_waitcnt lgkmcnt(6)
	v_mfma_f32_32x32x16_bf16 v[32:47], v[136:139], v[128:131], v[32:47]
	v_cvt_pk_bf16_f32 v101, v74, v75
	v_exp_f32_e32 v77, v77
	s_waitcnt lgkmcnt(5)
	v_mfma_f32_32x32x16_bf16 v[48:63], v[140:143], v[128:131], v[48:63]
	v_exp_f32_e32 v93, v93
	v_exp_f32_e32 v78, v78
	ds_read_b64_tr_b16 v[176:177], v162 offset:0
	ds_read_b64_tr_b16 v[178:179], v162 offset:1536
	v_mfma_f32_32x32x16_bf16 v[0:15], v[200:203], v[108:111], v[0:15]
	v_exp_f32_e32 v94, v94
	v_cvt_pk_bf16_f32 v102, v76, v77
	v_exp_f32_e32 v79, v79
	ds_read_b64_tr_b16 v[180:181], v162 offset:64
	ds_read_b64_tr_b16 v[182:183], v162 offset:1600
	s_waitcnt lgkmcnt(8)
	v_mfma_f32_32x32x16_bf16 v[32:47], v[144:147], v[132:135], v[32:47]
	v_exp_f32_e32 v95, v95
	v_cvt_pk_bf16_f32 v103, v78, v79
	ds_read_b64_tr_b16 v[184:185], v162 offset:6144
	ds_read_b64_tr_b16 v[186:187], v162 offset:7680
	v_mfma_f32_32x32x16_bf16 v[16:31], v[204:207], v[108:111], v[16:31]
	ds_read_b64_tr_b16 v[188:189], v162 offset:6208
	ds_read_b64_tr_b16 v[190:191], v162 offset:7744
	s_waitcnt lgkmcnt(8)
	v_mfma_f32_32x32x16_bf16 v[48:63], v[148:151], v[132:135], v[48:63]
	v_mfma_f32_16x16x32_bf16 v[234:237], v[246:249], v[108:111], v[234:237]
	v_cvt_pk_bf16_f32 v108, v88, v89
	v_cvt_pk_bf16_f32 v109, v90, v91
	v_cvt_pk_bf16_f32 v110, v92, v93
	v_cvt_pk_bf16_f32 v111, v94, v95
	s_cmp_lg_u32 s9, 0
	s_cbranch_scc0 .Lamla_noresc_3
	s_nop 15
	v_mul_f32_e32 v0, v0, v166
	v_mul_f32_e32 v1, v1, v166
	v_mul_f32_e32 v2, v2, v166
	v_mul_f32_e32 v3, v3, v166
	v_mul_f32_e32 v4, v4, v166
	v_mul_f32_e32 v5, v5, v166
	v_mul_f32_e32 v6, v6, v166
	v_mul_f32_e32 v7, v7, v166
	v_mul_f32_e32 v8, v8, v166
	v_mul_f32_e32 v9, v9, v166
	v_mul_f32_e32 v10, v10, v166
	v_mul_f32_e32 v11, v11, v166
	v_mul_f32_e32 v12, v12, v166
	v_mul_f32_e32 v13, v13, v166
	v_mul_f32_e32 v14, v14, v166
	v_mul_f32_e32 v15, v15, v166
	v_mul_f32_e32 v16, v16, v166
	v_mul_f32_e32 v17, v17, v166
	v_mul_f32_e32 v18, v18, v166
	v_mul_f32_e32 v19, v19, v166
	v_mul_f32_e32 v20, v20, v166
	v_mul_f32_e32 v21, v21, v166
	v_mul_f32_e32 v22, v22, v166
	v_mul_f32_e32 v23, v23, v166
	v_mul_f32_e32 v24, v24, v166
	v_mul_f32_e32 v25, v25, v166
	v_mul_f32_e32 v26, v26, v166
	v_mul_f32_e32 v27, v27, v166
	v_mul_f32_e32 v28, v28, v166
	v_mul_f32_e32 v29, v29, v166
	v_mul_f32_e32 v30, v30, v166
	v_mul_f32_e32 v31, v31, v166
	v_add_u32_e32 v170, 64, v175
	ds_bpermute_b32 v173, v170, v166
	v_mul_f32_e32 v234, v234, v166
	s_waitcnt lgkmcnt(0)
	v_mul_f32_e32 v235, v235, v173
.Lamla_noresc_3:
	s_nop 6
	s_barrier
	ds_read_b128 v[136:139], v243 offset:13312
	ds_read_b128 v[140:143], v243 offset:19968
	ds_read_b128 v[144:147], v243 offset:13344
	ds_read_b128 v[148:151], v243 offset:20000
	s_waitcnt lgkmcnt(10)
	v_mfma_f32_32x32x16_bf16 v[0:15], v[176:179], v[96:99], v[0:15]
	v_max3_f32 v168, v32, v33, v34
	v_max3_f32 v170, v48, v49, v50
	v_max3_f32 v168, v168, v35, v36
	v_max3_f32 v170, v170, v51, v52
	v_max3_f32 v168, v168, v37, v38
	s_mov_b32 s55, s52
	s_mov_b32 s52, s53
	s_mov_b32 s53, s54
	s_mov_b32 s54, s55
	s_mov_b32 s9, 0
	s_waitcnt lgkmcnt(8)
	v_mfma_f32_32x32x16_bf16 v[16:31], v[180:183], v[96:99], v[16:31]
	v_max3_f32 v170, v170, v53, v54
	v_max3_f32 v168, v168, v39, v40
	v_max3_f32 v170, v170, v55, v56
	v_max3_f32 v168, v168, v41, v42
	global_load_dwordx4 v[208:211], v167, s[2:3]
	global_load_dwordx2 v[216:217], v165, s[10:11]
	global_load_dwordx4 v[212:215], v167, s[4:5]
	s_add_u32 s2, s2, 0x2000
	s_addc_u32 s3, s3, 0
	s_add_u32 s10, s10, 0x1000
	s_addc_u32 s11, s11, 0
	s_add_u32 s4, s4, 0x2000
	s_addc_u32 s5, s5, 0
	v_add_u32_e32 v163, s53, v240
	v_add_u32_e32 v164, s54, v241
	v_mfma_f32_16x16x32_bf16 v[234:237], v[246:249], v[96:99], v[234:237]
	v_max3_f32 v170, v170, v57, v58
	v_max3_f32 v168, v168, v43, v44
	v_max3_f32 v170, v170, v59, v60
	v_max3_f32 v168, v168, v45, v46
	v_max3_f32 v170, v170, v61, v62
	v_max3_f32 v168, v168, v170, v47
	v_max_f32_e32 v168, v168, v63
	v_cmp_lt_f32_e32 vcc, 0x41000000, v168
	s_cbranch_vccz .Lamla_nors_4
	v_mov_b32_e32 v170, v168
	s_nop 1
	v_permlane32_swap_b32_e32 v168, v170
	v_max_f32_e32 v168, v168, v170
	v_max_f32_e32 v170, 0, v168
	v_exp_f32_e64 v166, -v170
	v_sub_f32_e32 v218, v218, v170
	v_sub_f32_e32 v219, v219, v170
	v_sub_f32_e32 v220, v220, v170
	v_sub_f32_e32 v221, v221, v170
	v_sub_f32_e32 v222, v222, v170
	v_sub_f32_e32 v223, v223, v170
	v_sub_f32_e32 v224, v224, v170
	v_sub_f32_e32 v225, v225, v170
	v_sub_f32_e32 v226, v226, v170
	v_sub_f32_e32 v227, v227, v170
	v_sub_f32_e32 v228, v228, v170
	v_sub_f32_e32 v229, v229, v170
	v_sub_f32_e32 v230, v230, v170
	v_sub_f32_e32 v231, v231, v170
	v_sub_f32_e32 v232, v232, v170
	v_sub_f32_e32 v233, v233, v170
	v_sub_f32_e32 v32, v32, v170
	v_sub_f32_e32 v33, v33, v170
	v_sub_f32_e32 v34, v34, v170
	v_sub_f32_e32 v35, v35, v170
	v_sub_f32_e32 v36, v36, v170
	v_sub_f32_e32 v37, v37, v170
	v_sub_f32_e32 v38, v38, v170
	v_sub_f32_e32 v39, v39, v170
	v_sub_f32_e32 v40, v40, v170
	v_sub_f32_e32 v41, v41, v170
	v_sub_f32_e32 v42, v42, v170
	v_sub_f32_e32 v43, v43, v170
	v_sub_f32_e32 v44, v44, v170
	v_sub_f32_e32 v45, v45, v170
	v_sub_f32_e32 v46, v46, v170
	v_sub_f32_e32 v47, v47, v170
	v_sub_f32_e32 v48, v48, v170
	v_sub_f32_e32 v49, v49, v170
	v_sub_f32_e32 v50, v50, v170
	v_sub_f32_e32 v51, v51, v170
	v_sub_f32_e32 v52, v52, v170
	v_sub_f32_e32 v53, v53, v170
	v_sub_f32_e32 v54, v54, v170
	v_sub_f32_e32 v55, v55, v170
	v_sub_f32_e32 v56, v56, v170
	v_sub_f32_e32 v57, v57, v170
	v_sub_f32_e32 v58, v58, v170
	v_sub_f32_e32 v59, v59, v170
	v_sub_f32_e32 v60, v60, v170
	v_sub_f32_e32 v61, v61, v170
	v_sub_f32_e32 v62, v62, v170
	v_sub_f32_e32 v63, v63, v170
	s_mov_b32 s9, 1
.Lamla_nors_4:
	s_waitcnt lgkmcnt(3)
	v_mfma_f32_32x32x16_bf16 v[64:79], v[136:139], v[112:115], v[218:233]
	v_exp_f32_e32 v32, v32
	v_exp_f32_e32 v48, v48
	ds_read_b128 v[136:139], v243 offset:13376
	ds_read_b64_tr_b16 v[192:193], v162 offset:3072
	ds_read_b64_tr_b16 v[194:195], v162 offset:4608
	s_waitcnt lgkmcnt(5)
	v_mfma_f32_32x32x16_bf16 v[80:95], v[140:143], v[112:115], v[218:233]
	v_exp_f32_e32 v33, v33
	v_exp_f32_e32 v49, v49
	ds_read_b128 v[140:143], v243 offset:20032
	ds_read_b64_tr_b16 v[196:197], v162 offset:3136
	ds_read_b64_tr_b16 v[198:199], v162 offset:4672
	v_mfma_f32_32x32x16_bf16 v[0:15], v[184:187], v[104:107], v[0:15]
	v_exp_f32_e32 v34, v34
	v_exp_f32_e32 v50, v50
	ds_read_b64_tr_b16 v[200:201], v162 offset:9216
	ds_read_b64_tr_b16 v[202:203], v162 offset:10752
	s_waitcnt lgkmcnt(9)
	v_mfma_f32_32x32x16_bf16 v[64:79], v[144:147], v[116:119], v[64:79]
	v_cvt_pk_bf16_f32 v96, v32, v33
	v_exp_f32_e32 v35, v35
	v_exp_f32_e32 v51, v51
	ds_read_b128 v[144:147], v243 offset:13408
	ds_read_b64_tr_b16 v[204:205], v162 offset:9280
	ds_read_b64_tr_b16 v[206:207], v162 offset:10816
	v_mfma_f32_32x32x16_bf16 v[16:31], v[188:191], v[104:107], v[16:31]
	v_exp_f32_e32 v36, v36
	v_exp_f32_e32 v52, v52
	s_waitcnt lgkmcnt(11)
	v_mfma_f32_32x32x16_bf16 v[80:95], v[148:151], v[116:119], v[80:95]
	v_cvt_pk_bf16_f32 v97, v34, v35
	v_exp_f32_e32 v37, v37
	ds_read_b128 v[148:151], v243 offset:20064
	v_mfma_f32_16x16x32_bf16 v[234:237], v[246:249], v[104:107], v[234:237]
	v_cvt_pk_bf16_f32 v104, v48, v49
	v_cvt_pk_bf16_f32 v105, v50, v51
	v_exp_f32_e32 v53, v53
	v_exp_f32_e32 v38, v38
	s_waitcnt lgkmcnt(11)
	v_mfma_f32_32x32x16_bf16 v[64:79], v[136:139], v[120:123], v[64:79]
	v_exp_f32_e32 v54, v54
	v_cvt_pk_bf16_f32 v98, v36, v37
	v_cvt_pk_bf16_f32 v106, v52, v53
	ds_read_b128 v[136:139], v243 offset:13440
	s_waitcnt lgkmcnt(9)
	v_mfma_f32_32x32x16_bf16 v[80:95], v[140:143], v[120:123], v[80:95]
	v_exp_f32_e32 v39, v39
	v_exp_f32_e32 v55, v55
	ds_read_b128 v[140:143], v243 offset:20096
	v_mfma_f32_32x32x16_bf16 v[0:15], v[192:195], v[100:103], v[0:15]
	v_exp_f32_e32 v40, v40
	v_exp_f32_e32 v56, v56
	v_cvt_pk_bf16_f32 v99, v38, v39
	s_waitcnt lgkmcnt(5)
	v_mfma_f32_32x32x16_bf16 v[64:79], v[144:147], v[124:127], v[64:79]
	v_cvt_pk_bf16_f32 v107, v54, v55
	v_exp_f32_e32 v41, v41
	v_exp_f32_e32 v57, v57
	ds_read_b128 v[144:147], v243 offset:13472
	v_mfma_f32_32x32x16_bf16 v[16:31], v[196:199], v[100:103], v[16:31]
	v_exp_f32_e32 v42, v42
	v_exp_f32_e32 v58, v58
	s_waitcnt vmcnt(5)
	ds_write_b128 v238, v[152:155]
	s_waitcnt vmcnt(4)
	ds_write_b64 v239, v[160:161]
	s_waitcnt vmcnt(3)
	ds_write_b128 v164, v[156:159]
	s_waitcnt lgkmcnt(6)
	v_mfma_f32_32x32x16_bf16 v[80:95], v[148:151], v[124:127], v[80:95]
	v_exp_f32_e32 v43, v43
	v_exp_f32_e32 v59, v59
	ds_read_b128 v[148:151], v243 offset:20128
	v_mfma_f32_16x16x32_bf16 v[234:237], v[246:249], v[100:103], v[234:237]
	v_cvt_pk_bf16_f32 v100, v40, v41
	v_exp_f32_e32 v44, v44
	v_exp_f32_e32 v60, v60
	s_waitcnt lgkmcnt(6)
	v_mfma_f32_32x32x16_bf16 v[64:79], v[136:139], v[128:131], v[64:79]
	v_cvt_pk_bf16_f32 v101, v42, v43
	v_exp_f32_e32 v45, v45
	s_waitcnt lgkmcnt(5)
	v_mfma_f32_32x32x16_bf16 v[80:95], v[140:143], v[128:131], v[80:95]
	v_exp_f32_e32 v61, v61
	v_exp_f32_e32 v46, v46
	ds_read_b64_tr_b16 v[176:177], v163 offset:0
	ds_read_b64_tr_b16 v[178:179], v163 offset:1536
	v_mfma_f32_32x32x16_bf16 v[0:15], v[200:203], v[108:111], v[0:15]
	v_exp_f32_e32 v62, v62
	v_cvt_pk_bf16_f32 v102, v44, v45
	v_exp_f32_e32 v47, v47
	ds_read_b64_tr_b16 v[180:181], v163 offset:64
	ds_read_b64_tr_b16 v[182:183], v163 offset:1600
	s_waitcnt lgkmcnt(8)
	v_mfma_f32_32x32x16_bf16 v[64:79], v[144:147], v[132:135], v[64:79]
	v_exp_f32_e32 v63, v63
	v_cvt_pk_bf16_f32 v103, v46, v47
	ds_read_b64_tr_b16 v[184:185], v163 offset:6144
	ds_read_b64_tr_b16 v[186:187], v163 offset:7680
	v_mfma_f32_32x32x16_bf16 v[16:31], v[204:207], v[108:111], v[16:31]
	ds_read_b64_tr_b16 v[188:189], v163 offset:6208
	ds_read_b64_tr_b16 v[190:191], v163 offset:7744
	s_waitcnt lgkmcnt(8)
	v_mfma_f32_32x32x16_bf16 v[80:95], v[148:151], v[132:135], v[80:95]
	v_mfma_f32_16x16x32_bf16 v[234:237], v[246:249], v[108:111], v[234:237]
	v_cvt_pk_bf16_f32 v108, v56, v57
	v_cvt_pk_bf16_f32 v109, v58, v59
	v_cvt_pk_bf16_f32 v110, v60, v61
	v_cvt_pk_bf16_f32 v111, v62, v63
	s_cmp_lg_u32 s9, 0
	s_cbranch_scc0 .Lamla_noresc_5
	s_nop 15
	v_mul_f32_e32 v0, v0, v166
	v_mul_f32_e32 v1, v1, v166
	v_mul_f32_e32 v2, v2, v166
	v_mul_f32_e32 v3, v3, v166
	v_mul_f32_e32 v4, v4, v166
	v_mul_f32_e32 v5, v5, v166
	v_mul_f32_e32 v6, v6, v166
	v_mul_f32_e32 v7, v7, v166
	v_mul_f32_e32 v8, v8, v166
	v_mul_f32_e32 v9, v9, v166
	v_mul_f32_e32 v10, v10, v166
	v_mul_f32_e32 v11, v11, v166
	v_mul_f32_e32 v12, v12, v166
	v_mul_f32_e32 v13, v13, v166
	v_mul_f32_e32 v14, v14, v166
	v_mul_f32_e32 v15, v15, v166
	v_mul_f32_e32 v16, v16, v166
	v_mul_f32_e32 v17, v17, v166
	v_mul_f32_e32 v18, v18, v166
	v_mul_f32_e32 v19, v19, v166
	v_mul_f32_e32 v20, v20, v166
	v_mul_f32_e32 v21, v21, v166
	v_mul_f32_e32 v22, v22, v166
	v_mul_f32_e32 v23, v23, v166
	v_mul_f32_e32 v24, v24, v166
	v_mul_f32_e32 v25, v25, v166
	v_mul_f32_e32 v26, v26, v166
	v_mul_f32_e32 v27, v27, v166
	v_mul_f32_e32 v28, v28, v166
	v_mul_f32_e32 v29, v29, v166
	v_mul_f32_e32 v30, v30, v166
	v_mul_f32_e32 v31, v31, v166
	v_add_u32_e32 v170, 64, v175
	ds_bpermute_b32 v173, v170, v166
	v_mul_f32_e32 v234, v234, v166
	s_waitcnt lgkmcnt(0)
	v_mul_f32_e32 v235, v235, v173

; #define AT_STEP(SC0, SC1, SN0, SN1, t, DOK, DOV) do { \
;             if (DOK) AT_GLOADK(((t) + 2) * 64); \
;             if (DOV) { AT_GLOADV(((t) + 1) * 64); AT_QK(SN0, SN1, ((t) + 1) & 1); } \
;             AT_SMPV(SC0, SC1, (t) & 1); \
;             if (DOK) AT_WRITEK((t) & 1); \
;             if (DOV) AT_WRITEV(((t) + 1) & 1); \
;             __syncthreads(); } while (0)
; template <bool MLA>
; DI void attn_phase(const int TID, const int BID, LAS unsigned char* lds, const Params& p, bool need_ctx) {
;     ...
;         AT_STEP(sa0, sa1, sb0, sb1, t, false, true);
;         AT_STEP(sb0, sb1, sa0, sa1, t + 1, false, false);
.Lamla_tail:
	ds_read_b128 v[136:139], v243 offset:0
	ds_read_b128 v[140:143], v243 offset:6656
	ds_read_b128 v[144:147], v243 offset:32
	ds_read_b128 v[148:151], v243 offset:6688
	s_waitcnt lgkmcnt(10)
	v_mfma_f32_32x32x16_bf16 v[0:15], v[176:179], v[96:99], v[0:15]
	v_max3_f32 v168, v64, v65, v66
	v_max3_f32 v170, v80, v81, v82
	v_max3_f32 v168, v168, v67, v68
	v_max3_f32 v170, v170, v83, v84
	v_max3_f32 v168, v168, v69, v70
	s_mov_b32 s55, s52
	s_mov_b32 s52, s53
	s_mov_b32 s53, s54
	s_mov_b32 s54, s55
	s_mov_b32 s9, 0
	s_waitcnt lgkmcnt(8)
	v_mfma_f32_32x32x16_bf16 v[16:31], v[180:183], v[96:99], v[16:31]
	v_max3_f32 v170, v170, v85, v86
	v_max3_f32 v168, v168, v71, v72
	v_max3_f32 v170, v170, v87, v88
	v_max3_f32 v168, v168, v73, v74
	global_load_dwordx4 v[156:159], v167, s[4:5]
	s_add_u32 s4, s4, 0x2000
	s_addc_u32 s5, s5, 0
	v_add_u32_e32 v162, s53, v240
	v_add_u32_e32 v164, s54, v241
	v_mfma_f32_16x16x32_bf16 v[234:237], v[246:249], v[96:99], v[234:237]
	v_max3_f32 v170, v170, v89, v90
	v_max3_f32 v168, v168, v75, v76
	v_max3_f32 v170, v170, v91, v92
	v_max3_f32 v168, v168, v77, v78
	v_max3_f32 v170, v170, v93, v94
	v_max3_f32 v168, v168, v170, v79
	v_max_f32_e32 v168, v168, v95
	v_cmp_lt_f32_e32 vcc, 0x41000000, v168
	s_cbranch_vccz .Lamla_nors_6
	v_mov_b32_e32 v170, v168
	s_nop 1
	v_permlane32_swap_b32_e32 v168, v170
	v_max_f32_e32 v168, v168, v170
	v_max_f32_e32 v170, 0, v168
	v_exp_f32_e64 v166, -v170
	v_sub_f32_e32 v218, v218, v170
	v_sub_f32_e32 v219, v219, v170
	v_sub_f32_e32 v220, v220, v170
	v_sub_f32_e32 v221, v221, v170
	v_sub_f32_e32 v222, v222, v170
	v_sub_f32_e32 v223, v223, v170
	v_sub_f32_e32 v224, v224, v170
	v_sub_f32_e32 v225, v225, v170
	v_sub_f32_e32 v226, v226, v170
	v_sub_f32_e32 v227, v227, v170
	v_sub_f32_e32 v228, v228, v170
	v_sub_f32_e32 v229, v229, v170
	v_sub_f32_e32 v230, v230, v170
	v_sub_f32_e32 v231, v231, v170
	v_sub_f32_e32 v232, v232, v170
	v_sub_f32_e32 v233, v233, v170
	v_sub_f32_e32 v64, v64, v170
	v_sub_f32_e32 v65, v65, v170
	v_sub_f32_e32 v66, v66, v170
	v_sub_f32_e32 v67, v67, v170
	v_sub_f32_e32 v68, v68, v170
	v_sub_f32_e32 v69, v69, v170
	v_sub_f32_e32 v70, v70, v170
	v_sub_f32_e32 v71, v71, v170
	v_sub_f32_e32 v72, v72, v170
	v_sub_f32_e32 v73, v73, v170
	v_sub_f32_e32 v74, v74, v170
	v_sub_f32_e32 v75, v75, v170
	v_sub_f32_e32 v76, v76, v170
	v_sub_f32_e32 v77, v77, v170
	v_sub_f32_e32 v78, v78, v170
	v_sub_f32_e32 v79, v79, v170
	v_sub_f32_e32 v80, v80, v170
	v_sub_f32_e32 v81, v81, v170
	v_sub_f32_e32 v82, v82, v170
	v_sub_f32_e32 v83, v83, v170
	v_sub_f32_e32 v84, v84, v170
	v_sub_f32_e32 v85, v85, v170
	v_sub_f32_e32 v86, v86, v170
	v_sub_f32_e32 v87, v87, v170
	v_sub_f32_e32 v88, v88, v170
	v_sub_f32_e32 v89, v89, v170
	v_sub_f32_e32 v90, v90, v170
	v_sub_f32_e32 v91, v91, v170
	v_sub_f32_e32 v92, v92, v170
	v_sub_f32_e32 v93, v93, v170
	v_sub_f32_e32 v94, v94, v170
	v_sub_f32_e32 v95, v95, v170
	s_mov_b32 s9, 1
.Lamla_nors_6:
	s_waitcnt lgkmcnt(3)
	v_mfma_f32_32x32x16_bf16 v[32:47], v[136:139], v[112:115], v[218:233]
	v_exp_f32_e32 v64, v64
	v_exp_f32_e32 v80, v80
	ds_read_b128 v[136:139], v243 offset:64
	ds_read_b64_tr_b16 v[192:193], v163 offset:3072
	ds_read_b64_tr_b16 v[194:195], v163 offset:4608
	s_waitcnt lgkmcnt(5)
	v_mfma_f32_32x32x16_bf16 v[48:63], v[140:143], v[112:115], v[218:233]
	v_exp_f32_e32 v65, v65
	v_exp_f32_e32 v81, v81
	ds_read_b128 v[140:143], v243 offset:6720
	ds_read_b64_tr_b16 v[196:197], v163 offset:3136
	ds_read_b64_tr_b16 v[198:199], v163 offset:4672
	v_mfma_f32_32x32x16_bf16 v[0:15], v[184:187], v[104:107], v[0:15]
	v_exp_f32_e32 v66, v66
	v_exp_f32_e32 v82, v82
	ds_read_b64_tr_b16 v[200:201], v163 offset:9216
	ds_read_b64_tr_b16 v[202:203], v163 offset:10752
	s_waitcnt lgkmcnt(9)
	v_mfma_f32_32x32x16_bf16 v[32:47], v[144:147], v[116:119], v[32:47]
	v_cvt_pk_bf16_f32 v96, v64, v65
	v_exp_f32_e32 v67, v67
	v_exp_f32_e32 v83, v83
	ds_read_b128 v[144:147], v243 offset:96
	ds_read_b64_tr_b16 v[204:205], v163 offset:9280
	ds_read_b64_tr_b16 v[206:207], v163 offset:10816
	v_mfma_f32_32x32x16_bf16 v[16:31], v[188:191], v[104:107], v[16:31]
	v_exp_f32_e32 v68, v68
	v_exp_f32_e32 v84, v84
	s_waitcnt lgkmcnt(11)
	v_mfma_f32_32x32x16_bf16 v[48:63], v[148:151], v[116:119], v[48:63]
	v_cvt_pk_bf16_f32 v97, v66, v67
	v_exp_f32_e32 v69, v69
	ds_read_b128 v[148:151], v243 offset:6752
	v_mfma_f32_16x16x32_bf16 v[234:237], v[246:249], v[104:107], v[234:237]
	v_cvt_pk_bf16_f32 v104, v80, v81
	v_cvt_pk_bf16_f32 v105, v82, v83
	v_exp_f32_e32 v85, v85
	v_exp_f32_e32 v70, v70
	s_waitcnt lgkmcnt(11)
	v_mfma_f32_32x32x16_bf16 v[32:47], v[136:139], v[120:123], v[32:47]
	v_exp_f32_e32 v86, v86
	v_cvt_pk_bf16_f32 v98, v68, v69
	v_cvt_pk_bf16_f32 v106, v84, v85
	ds_read_b128 v[136:139], v243 offset:128
	s_waitcnt lgkmcnt(9)
	v_mfma_f32_32x32x16_bf16 v[48:63], v[140:143], v[120:123], v[48:63]
	v_exp_f32_e32 v71, v71
	v_exp_f32_e32 v87, v87
	ds_read_b128 v[140:143], v243 offset:6784
	v_mfma_f32_32x32x16_bf16 v[0:15], v[192:195], v[100:103], v[0:15]
	v_exp_f32_e32 v72, v72
	v_exp_f32_e32 v88, v88
	v_cvt_pk_bf16_f32 v99, v70, v71
	s_waitcnt lgkmcnt(5)
	v_mfma_f32_32x32x16_bf16 v[32:47], v[144:147], v[124:127], v[32:47]
	v_cvt_pk_bf16_f32 v107, v86, v87
	v_exp_f32_e32 v73, v73
	v_exp_f32_e32 v89, v89
	ds_read_b128 v[144:147], v243 offset:160
	v_mfma_f32_32x32x16_bf16 v[16:31], v[196:199], v[100:103], v[16:31]
	v_exp_f32_e32 v74, v74
	v_exp_f32_e32 v90, v90
	s_waitcnt vmcnt(3)
	ds_write_b128 v238, v[208:211] offset:13312
	s_waitcnt vmcnt(2)
	ds_write_b64 v239, v[216:217] offset:13312
	s_waitcnt vmcnt(1)
	ds_write_b128 v164, v[212:215]
	s_waitcnt lgkmcnt(6)
; #define AT_STEP(SC0, SC1, SN0, SN1, t, DOK, DOV) do { \
;             if (DOK) AT_GLOADK(((t) + 2) * 64); \
;             if (DOV) { AT_GLOADV(((t) + 1) * 64); AT_QK(SN0, SN1, ((t) + 1) & 1); } \
;             AT_SMPV(SC0, SC1, (t) & 1); \
;             if (DOK) AT_WRITEK((t) & 1); \
;             if (DOV) AT_WRITEV(((t) + 1) & 1); \
;             __syncthreads(); } while (0)
; template <bool MLA>
; DI void attn_phase(const int TID, const int BID, LAS unsigned char* lds, const Params& p, bool need_ctx) {
;     ...
;         AT_STEP(sa0, sa1, sb0, sb1, t, false, true);
;         AT_STEP(sb0, sb1, sa0, sa1, t + 1, false, false);
	v_mfma_f32_32x32x16_bf16 v[48:63], v[148:151], v[124:127], v[48:63]
	v_exp_f32_e32 v75, v75
	v_exp_f32_e32 v91, v91
	ds_read_b128 v[148:151], v243 offset:6816
	v_mfma_f32_16x16x32_bf16 v[234:237], v[246:249], v[100:103], v[234:237]
	v_cvt_pk_bf16_f32 v100, v72, v73
	v_exp_f32_e32 v76, v76
	v_exp_f32_e32 v92, v92
	s_waitcnt lgkmcnt(6)
	v_mfma_f32_32x32x16_bf16 v[32:47], v[136:139], v[128:131], v[32:47]
	v_cvt_pk_bf16_f32 v101, v74, v75
	v_exp_f32_e32 v77, v77
	s_waitcnt lgkmcnt(5)
	v_mfma_f32_32x32x16_bf16 v[48:63], v[140:143], v[128:131], v[48:63]
	v_exp_f32_e32 v93, v93
	v_exp_f32_e32 v78, v78
	ds_read_b64_tr_b16 v[176:177], v162 offset:0
	ds_read_b64_tr_b16 v[178:179], v162 offset:1536
	v_mfma_f32_32x32x16_bf16 v[0:15], v[200:203], v[108:111], v[0:15]
	v_exp_f32_e32 v94, v94
	v_cvt_pk_bf16_f32 v102, v76, v77
	v_exp_f32_e32 v79, v79
	ds_read_b64_tr_b16 v[180:181], v162 offset:64
	ds_read_b64_tr_b16 v[182:183], v162 offset:1600
	s_waitcnt lgkmcnt(8)
	v_mfma_f32_32x32x16_bf16 v[32:47], v[144:147], v[132:135], v[32:47]
	v_exp_f32_e32 v95, v95
	v_cvt_pk_bf16_f32 v103, v78, v79
	ds_read_b64_tr_b16 v[184:185], v162 offset:6144
	ds_read_b64_tr_b16 v[186:187], v162 offset:7680
	v_mfma_f32_32x32x16_bf16 v[16:31], v[204:207], v[108:111], v[16:31]
	ds_read_b64_tr_b16 v[188:189], v162 offset:6208
	ds_read_b64_tr_b16 v[190:191], v162 offset:7744
	s_waitcnt lgkmcnt(8)
	v_mfma_f32_32x32x16_bf16 v[48:63], v[148:151], v[132:135], v[48:63]
	v_mfma_f32_16x16x32_bf16 v[234:237], v[246:249], v[108:111], v[234:237]
	v_cvt_pk_bf16_f32 v108, v88, v89
	v_cvt_pk_bf16_f32 v109, v90, v91
	v_cvt_pk_bf16_f32 v110, v92, v93
	v_cvt_pk_bf16_f32 v111, v94, v95
	s_cmp_lg_u32 s9, 0
	s_cbranch_scc0 .Lamla_noresc_7
	s_nop 15
	v_mul_f32_e32 v0, v0, v166
	v_mul_f32_e32 v1, v1, v166
	v_mul_f32_e32 v2, v2, v166
	v_mul_f32_e32 v3, v3, v166
	v_mul_f32_e32 v4, v4, v166
	v_mul_f32_e32 v5, v5, v166
	v_mul_f32_e32 v6, v6, v166
	v_mul_f32_e32 v7, v7, v166
	v_mul_f32_e32 v8, v8, v166
	v_mul_f32_e32 v9, v9, v166
	v_mul_f32_e32 v10, v10, v166
	v_mul_f32_e32 v11, v11, v166
	v_mul_f32_e32 v12, v12, v166
	v_mul_f32_e32 v13, v13, v166
	v_mul_f32_e32 v14, v14, v166
	v_mul_f32_e32 v15, v15, v166
	v_mul_f32_e32 v16, v16, v166
	v_mul_f32_e32 v17, v17, v166
	v_mul_f32_e32 v18, v18, v166
	v_mul_f32_e32 v19, v19, v166
	v_mul_f32_e32 v20, v20, v166
	v_mul_f32_e32 v21, v21, v166
	v_mul_f32_e32 v22, v22, v166
	v_mul_f32_e32 v23, v23, v166
	v_mul_f32_e32 v24, v24, v166
	v_mul_f32_e32 v25, v25, v166
	v_mul_f32_e32 v26, v26, v166
	v_mul_f32_e32 v27, v27, v166
	v_mul_f32_e32 v28, v28, v166
	v_mul_f32_e32 v29, v29, v166
	v_mul_f32_e32 v30, v30, v166
	v_mul_f32_e32 v31, v31, v166
	v_add_u32_e32 v170, 64, v175
	ds_bpermute_b32 v173, v170, v166
	v_mul_f32_e32 v234, v234, v166
	s_waitcnt lgkmcnt(0)
	v_mul_f32_e32 v235, v235, v173
.Lamla_noresc_7:
	s_nop 6
	s_barrier
	ds_read_b128 v[136:139], v243 offset:13312
	ds_read_b128 v[140:143], v243 offset:19968
	ds_read_b128 v[144:147], v243 offset:13344
	ds_read_b128 v[148:151], v243 offset:20000
	s_waitcnt lgkmcnt(10)
	v_mfma_f32_32x32x16_bf16 v[0:15], v[176:179], v[96:99], v[0:15]
	v_max3_f32 v168, v32, v33, v34
	v_max3_f32 v170, v48, v49, v50
	v_max3_f32 v168, v168, v35, v36
	v_max3_f32 v170, v170, v51, v52
	v_max3_f32 v168, v168, v37, v38
	s_mov_b32 s55, s52
	s_mov_b32 s52, s53
	s_mov_b32 s53, s54
	s_mov_b32 s54, s55
	s_mov_b32 s9, 0
	s_waitcnt lgkmcnt(8)
	v_mfma_f32_32x32x16_bf16 v[16:31], v[180:183], v[96:99], v[16:31]
	v_max3_f32 v170, v170, v53, v54
	v_max3_f32 v168, v168, v39, v40
	v_max3_f32 v170, v170, v55, v56
	v_max3_f32 v168, v168, v41, v42
	v_add_u32_e32 v163, s53, v240
	v_add_u32_e32 v164, s54, v241
	v_mfma_f32_16x16x32_bf16 v[234:237], v[246:249], v[96:99], v[234:237]
	v_max3_f32 v170, v170, v57, v58
	v_max3_f32 v168, v168, v43, v44
	v_max3_f32 v170, v170, v59, v60
	v_max3_f32 v168, v168, v45, v46
	v_max3_f32 v170, v170, v61, v62
	v_max3_f32 v168, v168, v170, v47
	v_max_f32_e32 v168, v168, v63
	v_cmp_lt_f32_e32 vcc, 0x41000000, v168
	s_cbranch_vccz .Lamla_nors_8
	v_mov_b32_e32 v170, v168
	s_nop 1
	v_permlane32_swap_b32_e32 v168, v170
	v_max_f32_e32 v168, v168, v170
	v_max_f32_e32 v170, 0, v168
	v_exp_f32_e64 v166, -v170
	v_sub_f32_e32 v218, v218, v170
	v_sub_f32_e32 v219, v219, v170
	v_sub_f32_e32 v220, v220, v170
	v_sub_f32_e32 v221, v221, v170
	v_sub_f32_e32 v222, v222, v170
	v_sub_f32_e32 v223, v223, v170
	v_sub_f32_e32 v224, v224, v170
	v_sub_f32_e32 v225, v225, v170
	v_sub_f32_e32 v226, v226, v170
	v_sub_f32_e32 v227, v227, v170
	v_sub_f32_e32 v228, v228, v170
	v_sub_f32_e32 v229, v229, v170
	v_sub_f32_e32 v230, v230, v170
	v_sub_f32_e32 v231, v231, v170
	v_sub_f32_e32 v232, v232, v170
	v_sub_f32_e32 v233, v233, v170
	v_sub_f32_e32 v32, v32, v170
	v_sub_f32_e32 v33, v33, v170
	v_sub_f32_e32 v34, v34, v170
	v_sub_f32_e32 v35, v35, v170
	v_sub_f32_e32 v36, v36, v170
	v_sub_f32_e32 v37, v37, v170
	v_sub_f32_e32 v38, v38, v170
	v_sub_f32_e32 v39, v39, v170
	v_sub_f32_e32 v40, v40, v170
	v_sub_f32_e32 v41, v41, v170
	v_sub_f32_e32 v42, v42, v170
	v_sub_f32_e32 v43, v43, v170
	v_sub_f32_e32 v44, v44, v170
	v_sub_f32_e32 v45, v45, v170
	v_sub_f32_e32 v46, v46, v170
	v_sub_f32_e32 v47, v47, v170
	v_sub_f32_e32 v48, v48, v170
	v_sub_f32_e32 v49, v49, v170
	v_sub_f32_e32 v50, v50, v170
	v_sub_f32_e32 v51, v51, v170
	v_sub_f32_e32 v52, v52, v170
	v_sub_f32_e32 v53, v53, v170
	v_sub_f32_e32 v54, v54, v170
	v_sub_f32_e32 v55, v55, v170
	v_sub_f32_e32 v56, v56, v170
	v_sub_f32_e32 v57, v57, v170
	v_sub_f32_e32 v58, v58, v170
	v_sub_f32_e32 v59, v59, v170
	v_sub_f32_e32 v60, v60, v170
	v_sub_f32_e32 v61, v61, v170
	v_sub_f32_e32 v62, v62, v170
	v_sub_f32_e32 v63, v63, v170
	s_mov_b32 s9, 1
; #define AT_STEP(SC0, SC1, SN0, SN1, t, DOK, DOV) do { \
;             if (DOK) AT_GLOADK(((t) + 2) * 64); \
;             if (DOV) { AT_GLOADV(((t) + 1) * 64); AT_QK(SN0, SN1, ((t) + 1) & 1); } \
;             AT_SMPV(SC0, SC1, (t) & 1); \
;             if (DOK) AT_WRITEK((t) & 1); \
;             if (DOV) AT_WRITEV(((t) + 1) & 1); \
;             __syncthreads(); } while (0)
; template <bool MLA>
; DI void attn_phase(const int TID, const int BID, LAS unsigned char* lds, const Params& p, bool need_ctx) {
;     ...
;         AT_STEP(sa0, sa1, sb0, sb1, t, false, true);
;         AT_STEP(sb0, sb1, sa0, sa1, t + 1, false, false);
.Lamla_nors_8:
	s_waitcnt lgkmcnt(3)
	v_mfma_f32_32x32x16_bf16 v[64:79], v[136:139], v[112:115], v[218:233]
	v_exp_f32_e32 v32, v32
	v_exp_f32_e32 v48, v48
	ds_read_b128 v[136:139], v243 offset:13376
	ds_read_b64_tr_b16 v[192:193], v162 offset:3072
	ds_read_b64_tr_b16 v[194:195], v162 offset:4608
	s_waitcnt lgkmcnt(5)
	v_mfma_f32_32x32x16_bf16 v[80:95], v[140:143], v[112:115], v[218:233]
	v_exp_f32_e32 v33, v33
	v_exp_f32_e32 v49, v49
	ds_read_b128 v[140:143], v243 offset:20032
	ds_read_b64_tr_b16 v[196:197], v162 offset:3136
	ds_read_b64_tr_b16 v[198:199], v162 offset:4672
	v_mfma_f32_32x32x16_bf16 v[0:15], v[184:187], v[104:107], v[0:15]
	v_exp_f32_e32 v34, v34
	v_exp_f32_e32 v50, v50
	ds_read_b64_tr_b16 v[200:201], v162 offset:9216
	ds_read_b64_tr_b16 v[202:203], v162 offset:10752
	s_waitcnt lgkmcnt(9)
	v_mfma_f32_32x32x16_bf16 v[64:79], v[144:147], v[116:119], v[64:79]
	v_cvt_pk_bf16_f32 v96, v32, v33
	v_exp_f32_e32 v35, v35
	v_exp_f32_e32 v51, v51
	ds_read_b128 v[144:147], v243 offset:13408
	ds_read_b64_tr_b16 v[204:205], v162 offset:9280
	ds_read_b64_tr_b16 v[206:207], v162 offset:10816
	v_mfma_f32_32x32x16_bf16 v[16:31], v[188:191], v[104:107], v[16:31]
	v_exp_f32_e32 v36, v36
	v_exp_f32_e32 v52, v52
	s_waitcnt lgkmcnt(11)
	v_mfma_f32_32x32x16_bf16 v[80:95], v[148:151], v[116:119], v[80:95]
	v_cvt_pk_bf16_f32 v97, v34, v35
	v_exp_f32_e32 v37, v37
	ds_read_b128 v[148:151], v243 offset:20064
	v_mfma_f32_16x16x32_bf16 v[234:237], v[246:249], v[104:107], v[234:237]
	v_cvt_pk_bf16_f32 v104, v48, v49
	v_cvt_pk_bf16_f32 v105, v50, v51
	v_exp_f32_e32 v53, v53
	v_exp_f32_e32 v38, v38
	s_waitcnt lgkmcnt(11)
	v_mfma_f32_32x32x16_bf16 v[64:79], v[136:139], v[120:123], v[64:79]
	v_exp_f32_e32 v54, v54
	v_cvt_pk_bf16_f32 v98, v36, v37
	v_cvt_pk_bf16_f32 v106, v52, v53
	ds_read_b128 v[136:139], v243 offset:13440
	s_waitcnt lgkmcnt(9)
	v_mfma_f32_32x32x16_bf16 v[80:95], v[140:143], v[120:123], v[80:95]
	v_exp_f32_e32 v39, v39
	v_exp_f32_e32 v55, v55
	ds_read_b128 v[140:143], v243 offset:20096
	v_mfma_f32_32x32x16_bf16 v[0:15], v[192:195], v[100:103], v[0:15]
	v_exp_f32_e32 v40, v40
	v_exp_f32_e32 v56, v56
	v_cvt_pk_bf16_f32 v99, v38, v39
	s_waitcnt lgkmcnt(5)
	v_mfma_f32_32x32x16_bf16 v[64:79], v[144:147], v[124:127], v[64:79]
	v_cvt_pk_bf16_f32 v107, v54, v55
	v_exp_f32_e32 v41, v41
	v_exp_f32_e32 v57, v57
	ds_read_b128 v[144:147], v243 offset:13472
	v_mfma_f32_32x32x16_bf16 v[16:31], v[196:199], v[100:103], v[16:31]
	v_exp_f32_e32 v42, v42
	v_exp_f32_e32 v58, v58
	s_waitcnt vmcnt(0)
	ds_write_b128 v164, v[156:159]
	s_waitcnt lgkmcnt(4)
	v_mfma_f32_32x32x16_bf16 v[80:95], v[148:151], v[124:127], v[80:95]
	v_exp_f32_e32 v43, v43
	v_exp_f32_e32 v59, v59
	ds_read_b128 v[148:151], v243 offset:20128
	v_mfma_f32_16x16x32_bf16 v[234:237], v[246:249], v[100:103], v[234:237]
	v_cvt_pk_bf16_f32 v100, v40, v41
	v_exp_f32_e32 v44, v44
	v_exp_f32_e32 v60, v60
	s_waitcnt lgkmcnt(4)
	v_mfma_f32_32x32x16_bf16 v[64:79], v[136:139], v[128:131], v[64:79]
	v_cvt_pk_bf16_f32 v101, v42, v43
	v_exp_f32_e32 v45, v45
	s_waitcnt lgkmcnt(3)
	v_mfma_f32_32x32x16_bf16 v[80:95], v[140:143], v[128:131], v[80:95]
	v_exp_f32_e32 v61, v61
	v_exp_f32_e32 v46, v46
	ds_read_b64_tr_b16 v[176:177], v163 offset:0
	ds_read_b64_tr_b16 v[178:179], v163 offset:1536
	v_mfma_f32_32x32x16_bf16 v[0:15], v[200:203], v[108:111], v[0:15]
	v_exp_f32_e32 v62, v62
	v_cvt_pk_bf16_f32 v102, v44, v45
	v_exp_f32_e32 v47, v47
	ds_read_b64_tr_b16 v[180:181], v163 offset:64
	ds_read_b64_tr_b16 v[182:183], v163 offset:1600
	s_waitcnt lgkmcnt(6)
	v_mfma_f32_32x32x16_bf16 v[64:79], v[144:147], v[132:135], v[64:79]
	v_exp_f32_e32 v63, v63
	v_cvt_pk_bf16_f32 v103, v46, v47
	ds_read_b64_tr_b16 v[184:185], v163 offset:6144
	ds_read_b64_tr_b16 v[186:187], v163 offset:7680
	v_mfma_f32_32x32x16_bf16 v[16:31], v[204:207], v[108:111], v[16:31]
	ds_read_b64_tr_b16 v[188:189], v163 offset:6208
	ds_read_b64_tr_b16 v[190:191], v163 offset:7744
	s_waitcnt lgkmcnt(8)
	v_mfma_f32_32x32x16_bf16 v[80:95], v[148:151], v[132:135], v[80:95]
	v_mfma_f32_16x16x32_bf16 v[234:237], v[246:249], v[108:111], v[234:237]
	v_cvt_pk_bf16_f32 v108, v56, v57
	v_cvt_pk_bf16_f32 v109, v58, v59
	v_cvt_pk_bf16_f32 v110, v60, v61
	v_cvt_pk_bf16_f32 v111, v62, v63
	s_cmp_lg_u32 s9, 0
	s_cbranch_scc0 .Lamla_noresc_9
	s_nop 15
	v_mul_f32_e32 v0, v0, v166
	v_mul_f32_e32 v1, v1, v166
	v_mul_f32_e32 v2, v2, v166
	v_mul_f32_e32 v3, v3, v166
	v_mul_f32_e32 v4, v4, v166
	v_mul_f32_e32 v5, v5, v166
	v_mul_f32_e32 v6, v6, v166
	v_mul_f32_e32 v7, v7, v166
	v_mul_f32_e32 v8, v8, v166
	v_mul_f32_e32 v9, v9, v166
	v_mul_f32_e32 v10, v10, v166
	v_mul_f32_e32 v11, v11, v166
	v_mul_f32_e32 v12, v12, v166
	v_mul_f32_e32 v13, v13, v166
	v_mul_f32_e32 v14, v14, v166
	v_mul_f32_e32 v15, v15, v166
	v_mul_f32_e32 v16, v16, v166
	v_mul_f32_e32 v17, v17, v166
	v_mul_f32_e32 v18, v18, v166
	v_mul_f32_e32 v19, v19, v166
	v_mul_f32_e32 v20, v20, v166
	v_mul_f32_e32 v21, v21, v166
	v_mul_f32_e32 v22, v22, v166
	v_mul_f32_e32 v23, v23, v166
	v_mul_f32_e32 v24, v24, v166
	v_mul_f32_e32 v25, v25, v166
	v_mul_f32_e32 v26, v26, v166
	v_mul_f32_e32 v27, v27, v166
	v_mul_f32_e32 v28, v28, v166
	v_mul_f32_e32 v29, v29, v166
	v_mul_f32_e32 v30, v30, v166
	v_mul_f32_e32 v31, v31, v166
	v_add_u32_e32 v170, 64, v175
	ds_bpermute_b32 v173, v170, v166
	v_mul_f32_e32 v234, v234, v166
	s_waitcnt lgkmcnt(0)
	v_mul_f32_e32 v235, v235, v173

; #define AT_STEP(SC0, SC1, SN0, SN1, t, DOK, DOV) do { \
;             if (DOK) AT_GLOADK(((t) + 2) * 64); \
;             if (DOV) { AT_GLOADV(((t) + 1) * 64); AT_QK(SN0, SN1, ((t) + 1) & 1); } \
;             AT_SMPV(SC0, SC1, (t) & 1); \
;             if (DOK) AT_WRITEK((t) & 1); \
;             if (DOV) AT_WRITEV(((t) + 1) & 1); \
;             __syncthreads(); } while (0)
; template <bool MLA>
; DI void attn_phase(const int TID, const int BID, LAS unsigned char* lds, const Params& p, bool need_ctx) {
;     ...
;         AT_STEP(sb0, sb1, sa0, sa1, t + 1, false, false);
.Lamla_nonext:
	ds_read_b64_tr_b16 v[192:193], v163 offset:3072
	ds_read_b64_tr_b16 v[194:195], v163 offset:4608
	ds_read_b64_tr_b16 v[196:197], v163 offset:3136
	ds_read_b64_tr_b16 v[198:199], v163 offset:4672
	s_waitcnt lgkmcnt(10)
	v_mfma_f32_32x32x16_bf16 v[0:15], v[176:179], v[96:99], v[0:15]
	v_max3_f32 v168, v64, v65, v66
	v_max3_f32 v170, v80, v81, v82
	v_max3_f32 v168, v168, v67, v68
	v_max3_f32 v170, v170, v83, v84
	v_max3_f32 v168, v168, v69, v70
	v_max3_f32 v170, v170, v85, v86
	v_max3_f32 v168, v168, v71, v72
	v_max3_f32 v170, v170, v87, v88
	v_max3_f32 v168, v168, v73, v74
	s_mov_b32 s55, s52
	s_mov_b32 s52, s53
	s_mov_b32 s53, s54
	s_mov_b32 s54, s55
	s_mov_b32 s9, 0
	ds_read_b64_tr_b16 v[200:201], v163 offset:9216
	ds_read_b64_tr_b16 v[202:203], v163 offset:10752
	ds_read_b64_tr_b16 v[204:205], v163 offset:9280
	ds_read_b64_tr_b16 v[206:207], v163 offset:10816
	s_waitcnt lgkmcnt(12)
	v_mfma_f32_32x32x16_bf16 v[16:31], v[180:183], v[96:99], v[16:31]
	v_max3_f32 v170, v170, v89, v90
	v_max3_f32 v168, v168, v75, v76
	v_max3_f32 v170, v170, v91, v92
	v_max3_f32 v168, v168, v77, v78
	v_max3_f32 v170, v170, v93, v94
	v_max3_f32 v168, v168, v170, v79
	v_max_f32_e32 v168, v168, v95
	v_cmp_lt_f32_e32 vcc, 0x41000000, v168
	s_cbranch_vccz .Lamla_nors_10
	v_mov_b32_e32 v170, v168
	s_nop 1
	v_permlane32_swap_b32_e32 v168, v170
	v_max_f32_e32 v168, v168, v170
	v_max_f32_e32 v170, 0, v168
	v_exp_f32_e64 v166, -v170
	v_sub_f32_e32 v218, v218, v170
	v_sub_f32_e32 v219, v219, v170
	v_sub_f32_e32 v220, v220, v170
	v_sub_f32_e32 v221, v221, v170
	v_sub_f32_e32 v222, v222, v170
	v_sub_f32_e32 v223, v223, v170
	v_sub_f32_e32 v224, v224, v170
	v_sub_f32_e32 v225, v225, v170
	v_sub_f32_e32 v226, v226, v170
	v_sub_f32_e32 v227, v227, v170
	v_sub_f32_e32 v228, v228, v170
	v_sub_f32_e32 v229, v229, v170
	v_sub_f32_e32 v230, v230, v170
	v_sub_f32_e32 v231, v231, v170
	v_sub_f32_e32 v232, v232, v170
	v_sub_f32_e32 v233, v233, v170
	v_sub_f32_e32 v64, v64, v170
	v_sub_f32_e32 v65, v65, v170
	v_sub_f32_e32 v66, v66, v170
	v_sub_f32_e32 v67, v67, v170
	v_sub_f32_e32 v68, v68, v170
	v_sub_f32_e32 v69, v69, v170
	v_sub_f32_e32 v70, v70, v170
	v_sub_f32_e32 v71, v71, v170
	v_sub_f32_e32 v72, v72, v170
	v_sub_f32_e32 v73, v73, v170
	v_sub_f32_e32 v74, v74, v170
	v_sub_f32_e32 v75, v75, v170
	v_sub_f32_e32 v76, v76, v170
	v_sub_f32_e32 v77, v77, v170
	v_sub_f32_e32 v78, v78, v170
	v_sub_f32_e32 v79, v79, v170
	v_sub_f32_e32 v80, v80, v170
	v_sub_f32_e32 v81, v81, v170
	v_sub_f32_e32 v82, v82, v170
	v_sub_f32_e32 v83, v83, v170
	v_sub_f32_e32 v84, v84, v170
	v_sub_f32_e32 v85, v85, v170
	v_sub_f32_e32 v86, v86, v170
	v_sub_f32_e32 v87, v87, v170
	v_sub_f32_e32 v88, v88, v170
	v_sub_f32_e32 v89, v89, v170
	v_sub_f32_e32 v90, v90, v170
	v_sub_f32_e32 v91, v91, v170
	v_sub_f32_e32 v92, v92, v170
	v_sub_f32_e32 v93, v93, v170
	v_sub_f32_e32 v94, v94, v170
	v_sub_f32_e32 v95, v95, v170
	s_mov_b32 s9, 1
.Lamla_nors_10:
	v_add_u32_e32 v162, s53, v240
	v_mfma_f32_16x16x32_bf16 v[234:237], v[246:249], v[96:99], v[234:237]
	v_exp_f32_e32 v64, v64
	v_exp_f32_e32 v80, v80
	v_exp_f32_e32 v65, v65
	v_exp_f32_e32 v81, v81
	s_waitcnt lgkmcnt(10)
	v_mfma_f32_32x32x16_bf16 v[0:15], v[184:187], v[104:107], v[0:15]
	v_exp_f32_e32 v66, v66
	v_exp_f32_e32 v82, v82
	v_cvt_pk_bf16_f32 v96, v64, v65
	v_exp_f32_e32 v67, v67
	s_waitcnt lgkmcnt(8)
	v_mfma_f32_32x32x16_bf16 v[16:31], v[188:191], v[104:107], v[16:31]
	v_exp_f32_e32 v83, v83
	v_exp_f32_e32 v68, v68
	v_exp_f32_e32 v84, v84
	v_cvt_pk_bf16_f32 v97, v66, v67
	v_exp_f32_e32 v69, v69
	v_mfma_f32_16x16x32_bf16 v[234:237], v[246:249], v[104:107], v[234:237]
	v_cvt_pk_bf16_f32 v104, v80, v81
	v_cvt_pk_bf16_f32 v105, v82, v83
	v_exp_f32_e32 v85, v85
	v_exp_f32_e32 v70, v70
	v_exp_f32_e32 v86, v86
	v_cvt_pk_bf16_f32 v98, v68, v69
	s_waitcnt lgkmcnt(6)
	v_mfma_f32_32x32x16_bf16 v[0:15], v[192:195], v[100:103], v[0:15]
	v_cvt_pk_bf16_f32 v106, v84, v85
	v_exp_f32_e32 v71, v71
	v_exp_f32_e32 v87, v87
	v_exp_f32_e32 v72, v72
	v_exp_f32_e32 v88, v88
	ds_read_b64_tr_b16 v[176:177], v162 offset:0
	ds_read_b64_tr_b16 v[178:179], v162 offset:1536
	s_waitcnt lgkmcnt(6)
	v_mfma_f32_32x32x16_bf16 v[16:31], v[196:199], v[100:103], v[16:31]
	v_cvt_pk_bf16_f32 v99, v70, v71
	v_cvt_pk_bf16_f32 v107, v86, v87
	v_exp_f32_e32 v73, v73
	v_exp_f32_e32 v89, v89
	v_exp_f32_e32 v74, v74
	ds_read_b64_tr_b16 v[180:181], v162 offset:64
	ds_read_b64_tr_b16 v[182:183], v162 offset:1600
	v_mfma_f32_16x16x32_bf16 v[234:237], v[246:249], v[100:103], v[234:237]
	v_exp_f32_e32 v90, v90
	v_cvt_pk_bf16_f32 v100, v72, v73
	v_exp_f32_e32 v75, v75
	v_exp_f32_e32 v91, v91
	v_exp_f32_e32 v76, v76
	ds_read_b64_tr_b16 v[184:185], v162 offset:6144
	ds_read_b64_tr_b16 v[186:187], v162 offset:7680
	s_waitcnt lgkmcnt(8)
	v_mfma_f32_32x32x16_bf16 v[0:15], v[200:203], v[108:111], v[0:15]
	v_exp_f32_e32 v92, v92
	v_cvt_pk_bf16_f32 v101, v74, v75
	v_exp_f32_e32 v77, v77
	v_exp_f32_e32 v93, v93
	ds_read_b64_tr_b16 v[188:189], v162 offset:6208
	ds_read_b64_tr_b16 v[190:191], v162 offset:7744
	s_waitcnt lgkmcnt(8)
	v_mfma_f32_32x32x16_bf16 v[16:31], v[204:207], v[108:111], v[16:31]
	v_exp_f32_e32 v78, v78
	v_exp_f32_e32 v94, v94
	v_cvt_pk_bf16_f32 v102, v76, v77
	v_exp_f32_e32 v79, v79
	v_exp_f32_e32 v95, v95
	v_mfma_f32_16x16x32_bf16 v[234:237], v[246:249], v[108:111], v[234:237]
	v_cvt_pk_bf16_f32 v108, v88, v89
	v_cvt_pk_bf16_f32 v109, v90, v91
	v_cvt_pk_bf16_f32 v110, v92, v93
	v_cvt_pk_bf16_f32 v103, v78, v79
	v_cvt_pk_bf16_f32 v111, v94, v95
	s_cmp_lg_u32 s9, 0
	s_cbranch_scc0 .Lamla_noresc_11
	s_nop 15
	v_mul_f32_e32 v0, v0, v166
	v_mul_f32_e32 v1, v1, v166
	v_mul_f32_e32 v2, v2, v166
	v_mul_f32_e32 v3, v3, v166
	v_mul_f32_e32 v4, v4, v166
	v_mul_f32_e32 v5, v5, v166
	v_mul_f32_e32 v6, v6, v166
	v_mul_f32_e32 v7, v7, v166
	v_mul_f32_e32 v8, v8, v166
	v_mul_f32_e32 v9, v9, v166
	v_mul_f32_e32 v10, v10, v166
	v_mul_f32_e32 v11, v11, v166
	v_mul_f32_e32 v12, v12, v166
	v_mul_f32_e32 v13, v13, v166
	v_mul_f32_e32 v14, v14, v166
	v_mul_f32_e32 v15, v15, v166
	v_mul_f32_e32 v16, v16, v166
	v_mul_f32_e32 v17, v17, v166
	v_mul_f32_e32 v18, v18, v166
	v_mul_f32_e32 v19, v19, v166
	v_mul_f32_e32 v20, v20, v166
	v_mul_f32_e32 v21, v21, v166
	v_mul_f32_e32 v22, v22, v166
	v_mul_f32_e32 v23, v23, v166
	v_mul_f32_e32 v24, v24, v166
	v_mul_f32_e32 v25, v25, v166
	v_mul_f32_e32 v26, v26, v166
	v_mul_f32_e32 v27, v27, v166
	v_mul_f32_e32 v28, v28, v166
	v_mul_f32_e32 v29, v29, v166
	v_mul_f32_e32 v30, v30, v166
	v_mul_f32_e32 v31, v31, v166
	v_add_u32_e32 v170, 64, v175
	ds_bpermute_b32 v173, v170, v166
	v_mul_f32_e32 v234, v234, v166
	s_waitcnt lgkmcnt(0)
	v_mul_f32_e32 v235, v235, v173

; #define AT_GLOADK(k0) do { kreg = *(const u32x4*)(Kb + (size_t)((k0) + (tid >> 3)) * 64 + (tid & 7) * 8); \
;             if (MLA) preg = *(const u32x2*)(Pb + (size_t)((k0) + (tid >> 3)) * 32 + (tid & 7) * 4); } while (0)
; #define AT_GLOADV(k0) do { vreg = *(const u32x4*)(Vb + (size_t)((k0) + (tid >> 3)) * 64 + (tid & 7) * 8); } while (0)
; #define AT_WRITEK(buf) do { *(LAS u32x4*)(lds + (buf) * KBUF + (tid >> 3) * KSTR + (tid & 7) * 16) = kreg; \
;             if (MLA) *(LAS u32x2*)(lds + (buf) * KBUF + (tid >> 3) * KSTR + 128 + (tid & 7) * 8) = preg; } while (0)
; #define AT_WRITEV(buf) do { *(LAS u32x4*)(lds + 2 * KBUF + (buf) * VBUF + (tid >> 3) * VSTR + (tid & 7) * 16) = vreg; } while (0)
; template <bool MLA>
; DI void attn_phase(const int TID, const int BID, LAS unsigned char* lds, const Params& p, bool need_ctx) {
;     ...
;         AT_GLOADK(0); AT_GLOADV(0); AT_WRITEK(0); AT_WRITEV(0);
;         AT_GLOADK(64); AT_WRITEK(1);
;         __syncthreads();
;         AT_QK(sa0, sa1, 0);
;         __syncthreads();
.Lagqa_prio:
	ds_read_b128 v[136:139], v243 offset:0
	ds_read_b128 v[140:143], v243 offset:4608
	ds_read_b128 v[144:147], v243 offset:32
	ds_read_b128 v[148:151], v243 offset:4640
	s_waitcnt lgkmcnt(3)
	v_mfma_f32_32x32x16_bf16 v[32:47], v[136:139], v[112:115], 0
	ds_read_b128 v[136:139], v243 offset:64
	s_waitcnt lgkmcnt(3)
	v_mfma_f32_32x32x16_bf16 v[48:63], v[140:143], v[112:115], 0
	ds_read_b128 v[140:143], v243 offset:4672
	s_waitcnt lgkmcnt(3)
	v_mfma_f32_32x32x16_bf16 v[32:47], v[144:147], v[116:119], v[32:47]
	ds_read_b128 v[144:147], v243 offset:96
	s_waitcnt lgkmcnt(3)
	v_mfma_f32_32x32x16_bf16 v[48:63], v[148:151], v[116:119], v[48:63]
	ds_read_b128 v[148:151], v243 offset:4704
	s_waitcnt lgkmcnt(3)
	v_mfma_f32_32x32x16_bf16 v[32:47], v[136:139], v[120:123], v[32:47]
	s_waitcnt lgkmcnt(2)
	v_mfma_f32_32x32x16_bf16 v[48:63], v[140:143], v[120:123], v[48:63]
	s_waitcnt lgkmcnt(1)
	v_mfma_f32_32x32x16_bf16 v[32:47], v[144:147], v[124:127], v[32:47]
	s_waitcnt lgkmcnt(0)
	v_mfma_f32_32x32x16_bf16 v[48:63], v[148:151], v[124:127], v[48:63]
	s_waitcnt lgkmcnt(0)
	s_nop 7
	s_barrier
	ds_read_b128 v[136:139], v243 offset:9216
	ds_read_b128 v[140:143], v243 offset:13824
	ds_read_b128 v[144:147], v243 offset:9248
	ds_read_b128 v[148:151], v243 offset:13856
	v_max3_f32 v168, v32, v33, v34
	v_max3_f32 v170, v48, v49, v50
	v_max3_f32 v168, v168, v35, v36
	v_max3_f32 v170, v170, v51, v52
	v_max3_f32 v168, v168, v37, v38
	v_max3_f32 v170, v170, v53, v54
	v_max3_f32 v168, v168, v39, v40
	v_max3_f32 v170, v170, v55, v56
	v_max3_f32 v168, v168, v41, v42
	v_max3_f32 v170, v170, v57, v58
	v_max3_f32 v168, v168, v43, v44
	v_max3_f32 v170, v170, v59, v60
	v_max3_f32 v168, v168, v45, v46
	v_max3_f32 v170, v170, v61, v62
	v_max3_f32 v168, v168, v170, v47
	v_max_f32_e32 v168, v168, v63
	v_mov_b32_e32 v170, v168
	s_nop 1
	v_permlane32_swap_b32_e32 v168, v170
	v_max_f32_e32 v168, v168, v170
	v_mov_b32_e32 v170, v168
	v_sub_f32_e32 v218, v218, v170
	v_sub_f32_e32 v219, v219, v170
	v_sub_f32_e32 v220, v220, v170
	v_sub_f32_e32 v221, v221, v170
	v_sub_f32_e32 v222, v222, v170
	v_sub_f32_e32 v223, v223, v170
	v_sub_f32_e32 v224, v224, v170
	v_sub_f32_e32 v225, v225, v170
	v_sub_f32_e32 v226, v226, v170
	v_sub_f32_e32 v227, v227, v170
	v_sub_f32_e32 v228, v228, v170
	v_sub_f32_e32 v229, v229, v170
	v_sub_f32_e32 v230, v230, v170
	v_sub_f32_e32 v231, v231, v170
	v_sub_f32_e32 v232, v232, v170
	v_sub_f32_e32 v233, v233, v170
	v_sub_f32_e32 v32, v32, v170
	v_sub_f32_e32 v33, v33, v170
	v_sub_f32_e32 v34, v34, v170
	v_sub_f32_e32 v35, v35, v170
	v_sub_f32_e32 v36, v36, v170
	v_sub_f32_e32 v37, v37, v170
	v_sub_f32_e32 v38, v38, v170
	v_sub_f32_e32 v39, v39, v170
	v_sub_f32_e32 v40, v40, v170
	v_sub_f32_e32 v41, v41, v170
	v_sub_f32_e32 v42, v42, v170
	v_sub_f32_e32 v43, v43, v170
	v_sub_f32_e32 v44, v44, v170
	v_sub_f32_e32 v45, v45, v170
	v_sub_f32_e32 v46, v46, v170
	v_sub_f32_e32 v47, v47, v170
	v_sub_f32_e32 v48, v48, v170
	v_sub_f32_e32 v49, v49, v170
	v_sub_f32_e32 v50, v50, v170
	v_sub_f32_e32 v51, v51, v170
	v_sub_f32_e32 v52, v52, v170
	v_sub_f32_e32 v53, v53, v170
	v_sub_f32_e32 v54, v54, v170
	v_sub_f32_e32 v55, v55, v170
	v_sub_f32_e32 v56, v56, v170
	v_sub_f32_e32 v57, v57, v170
	v_sub_f32_e32 v58, v58, v170
	v_sub_f32_e32 v59, v59, v170
	v_sub_f32_e32 v60, v60, v170
	v_sub_f32_e32 v61, v61, v170
	v_sub_f32_e32 v62, v62, v170
	v_sub_f32_e32 v63, v63, v170
	s_waitcnt lgkmcnt(3)
	v_mfma_f32_32x32x16_bf16 v[64:79], v[136:139], v[112:115], v[218:233]
	v_exp_f32_e32 v32, v32
	v_exp_f32_e32 v48, v48
	v_exp_f32_e32 v33, v33
	v_exp_f32_e32 v49, v49
	v_exp_f32_e32 v34, v34
	v_exp_f32_e32 v50, v50
	v_cvt_pk_bf16_f32 v96, v32, v33
	ds_read_b128 v[136:139], v243 offset:9280
	s_mov_b32 s55, s52
	s_mov_b32 s52, s53
	s_mov_b32 s53, s54
	s_mov_b32 s54, s55
	s_mov_b32 s9, 0
	s_waitcnt lgkmcnt(3)
	v_mfma_f32_32x32x16_bf16 v[80:95], v[140:143], v[112:115], v[218:233]
	v_cvt_pk_bf16_f32 v104, v48, v49
	v_exp_f32_e32 v35, v35
	v_exp_f32_e32 v51, v51
	v_exp_f32_e32 v36, v36
	v_exp_f32_e32 v52, v52
	v_cvt_pk_bf16_f32 v97, v34, v35
	v_cvt_pk_bf16_f32 v105, v50, v51
	v_exp_f32_e32 v37, v37
	ds_read_b128 v[140:143], v243 offset:13888
	global_load_dwordx4 v[208:211], v167, s[2:3]
	global_load_dwordx4 v[212:215], v167, s[4:5]
	s_add_u32 s2, s2, 0x2000
	s_addc_u32 s3, s3, 0
	s_add_u32 s4, s4, 0x2000
	s_addc_u32 s5, s5, 0
	v_add_u32_e32 v163, s53, v240
	v_add_u32_e32 v164, s54, v241
	s_waitcnt lgkmcnt(3)
	v_mfma_f32_32x32x16_bf16 v[64:79], v[144:147], v[116:119], v[64:79]
	v_exp_f32_e32 v53, v53
	v_exp_f32_e32 v38, v38
	v_exp_f32_e32 v54, v54
	v_cvt_pk_bf16_f32 v98, v36, v37
	v_cvt_pk_bf16_f32 v106, v52, v53
	v_exp_f32_e32 v39, v39
	v_exp_f32_e32 v55, v55
	ds_read_b128 v[144:147], v243 offset:9312
	ds_read_b64_tr_b16 v[176:177], v163 offset:0
	ds_read_b64_tr_b16 v[178:179], v163 offset:1536
	s_waitcnt lgkmcnt(5)
	v_mfma_f32_32x32x16_bf16 v[80:95], v[148:151], v[116:119], v[80:95]
	v_exp_f32_e32 v40, v40
	v_exp_f32_e32 v56, v56
	v_cvt_pk_bf16_f32 v99, v38, v39
	v_cvt_pk_bf16_f32 v107, v54, v55
	v_exp_f32_e32 v41, v41
	v_exp_f32_e32 v57, v57
	v_exp_f32_e32 v42, v42
	ds_read_b128 v[148:151], v243 offset:13920
	ds_read_b64_tr_b16 v[180:181], v163 offset:64
	ds_read_b64_tr_b16 v[182:183], v163 offset:1600
	s_waitcnt lgkmcnt(7)
	v_mfma_f32_32x32x16_bf16 v[64:79], v[136:139], v[120:123], v[64:79]
	v_exp_f32_e32 v58, v58
	v_cvt_pk_bf16_f32 v100, v40, v41
	v_cvt_pk_bf16_f32 v108, v56, v57
	v_exp_f32_e32 v43, v43
	v_exp_f32_e32 v59, v59
	v_exp_f32_e32 v44, v44
	v_exp_f32_e32 v60, v60
	ds_read_b64_tr_b16 v[184:185], v163 offset:6144
	ds_read_b64_tr_b16 v[186:187], v163 offset:7680
	s_waitcnt vmcnt(3)
	ds_write_b128 v238, v[152:155]
	s_waitcnt vmcnt(2)
	ds_write_b128 v164, v[156:159]
	s_waitcnt lgkmcnt(10)
	v_mfma_f32_32x32x16_bf16 v[80:95], v[140:143], v[120:123], v[80:95]
	v_cvt_pk_bf16_f32 v101, v42, v43
	v_cvt_pk_bf16_f32 v109, v58, v59
	v_exp_f32_e32 v45, v45
	v_exp_f32_e32 v61, v61
	v_exp_f32_e32 v46, v46
	v_exp_f32_e32 v62, v62
	v_cvt_pk_bf16_f32 v102, v44, v45
	v_cvt_pk_bf16_f32 v110, v60, v61
	ds_read_b64_tr_b16 v[188:189], v163 offset:6208
	ds_read_b64_tr_b16 v[190:191], v163 offset:7744
	s_waitcnt lgkmcnt(11)
	v_mfma_f32_32x32x16_bf16 v[64:79], v[144:147], v[124:127], v[64:79]
	v_exp_f32_e32 v47, v47
	v_exp_f32_e32 v63, v63
	v_cvt_pk_bf16_f32 v103, v46, v47
	v_cvt_pk_bf16_f32 v111, v62, v63
	s_waitcnt lgkmcnt(8)
	v_mfma_f32_32x32x16_bf16 v[80:95], v[148:151], v[124:127], v[80:95]
	s_nop 13
	s_waitcnt lgkmcnt(2)
	s_waitcnt lgkmcnt(0)
	s_barrier
	s_cmp_eq_u32 s7, 0
	s_cbranch_scc1 .Lagqa_tail
; #define AT_STEP(SC0, SC1, SN0, SN1, t, DOK, DOV) do { \
;             if (DOK) AT_GLOADK(((t) + 2) * 64); \
;             if (DOV) { AT_GLOADV(((t) + 1) * 64); AT_QK(SN0, SN1, ((t) + 1) & 1); } \
;             AT_SMPV(SC0, SC1, (t) & 1); \
;             if (DOK) AT_WRITEK((t) & 1); \
;             if (DOV) AT_WRITEV(((t) + 1) & 1); \
;             __syncthreads(); } while (0)
; template <bool MLA>
; DI void attn_phase(const int TID, const int BID, LAS unsigned char* lds, const Params& p, bool need_ctx) {
;     ...
;         for (; t < ntile - 2; t += 2) {
;             AT_STEP(sa0, sa1, sb0, sb1, t, true, true);
;             AT_STEP(sb0, sb1, sa0, sa1, t + 1, true, true);
.Lagqa_loop:
	ds_read_b128 v[136:139], v243 offset:0
	ds_read_b128 v[140:143], v243 offset:4608
	ds_read_b128 v[144:147], v243 offset:32
	ds_read_b128 v[148:151], v243 offset:4640
	s_waitcnt lgkmcnt(10)
	v_mfma_f32_32x32x16_bf16 v[0:15], v[176:179], v[96:99], v[0:15]
	v_max3_f32 v168, v64, v65, v66
	v_max3_f32 v170, v80, v81, v82
	v_max3_f32 v168, v168, v67, v68
	v_max3_f32 v170, v170, v83, v84
	v_max3_f32 v168, v168, v69, v70
	s_mov_b32 s55, s52
	s_mov_b32 s52, s53
	s_mov_b32 s53, s54
	s_mov_b32 s54, s55
	s_mov_b32 s9, 0
	s_waitcnt lgkmcnt(8)
	v_mfma_f32_32x32x16_bf16 v[16:31], v[180:183], v[96:99], v[16:31]
	v_max3_f32 v170, v170, v85, v86
	v_max3_f32 v168, v168, v71, v72
	v_max3_f32 v170, v170, v87, v88
	v_max3_f32 v168, v168, v73, v74
	v_max3_f32 v170, v170, v89, v90
	global_load_dwordx4 v[152:155], v167, s[2:3]
	global_load_dwordx4 v[156:159], v167, s[4:5]
	s_add_u32 s2, s2, 0x2000
	s_addc_u32 s3, s3, 0
	s_add_u32 s4, s4, 0x2000
	s_addc_u32 s5, s5, 0
	v_add_u32_e32 v162, s53, v240
	v_add_u32_e32 v164, s54, v241
	v_mfma_f32_16x16x32_bf16 v[234:237], v[246:249], v[96:99], v[234:237]
	v_max3_f32 v168, v168, v75, v76
	v_max3_f32 v170, v170, v91, v92
	v_max3_f32 v168, v168, v77, v78
	v_max3_f32 v170, v170, v93, v94
	v_max3_f32 v168, v168, v170, v79
	v_max_f32_e32 v168, v168, v95
	v_cmp_lt_f32_e32 vcc, 0x41000000, v168
	s_cbranch_vccz .Lagqa_nors_2
	v_mov_b32_e32 v170, v168
	s_nop 1
	v_permlane32_swap_b32_e32 v168, v170
	v_max_f32_e32 v168, v168, v170
	v_max_f32_e32 v170, 0, v168
	v_exp_f32_e64 v166, -v170
	v_sub_f32_e32 v218, v218, v170
	v_sub_f32_e32 v219, v219, v170
	v_sub_f32_e32 v220, v220, v170
	v_sub_f32_e32 v221, v221, v170
	v_sub_f32_e32 v222, v222, v170
	v_sub_f32_e32 v223, v223, v170
	v_sub_f32_e32 v224, v224, v170
	v_sub_f32_e32 v225, v225, v170
	v_sub_f32_e32 v226, v226, v170
	v_sub_f32_e32 v227, v227, v170
	v_sub_f32_e32 v228, v228, v170
	v_sub_f32_e32 v229, v229, v170
	v_sub_f32_e32 v230, v230, v170
	v_sub_f32_e32 v231, v231, v170
	v_sub_f32_e32 v232, v232, v170
	v_sub_f32_e32 v233, v233, v170
	v_sub_f32_e32 v64, v64, v170
	v_sub_f32_e32 v65, v65, v170
	v_sub_f32_e32 v66, v66, v170
	v_sub_f32_e32 v67, v67, v170
	v_sub_f32_e32 v68, v68, v170
	v_sub_f32_e32 v69, v69, v170
	v_sub_f32_e32 v70, v70, v170
	v_sub_f32_e32 v71, v71, v170
	v_sub_f32_e32 v72, v72, v170
	v_sub_f32_e32 v73, v73, v170
	v_sub_f32_e32 v74, v74, v170
	v_sub_f32_e32 v75, v75, v170
	v_sub_f32_e32 v76, v76, v170
	v_sub_f32_e32 v77, v77, v170
	v_sub_f32_e32 v78, v78, v170
	v_sub_f32_e32 v79, v79, v170
	v_sub_f32_e32 v80, v80, v170
	v_sub_f32_e32 v81, v81, v170
	v_sub_f32_e32 v82, v82, v170
	v_sub_f32_e32 v83, v83, v170
	v_sub_f32_e32 v84, v84, v170
	v_sub_f32_e32 v85, v85, v170
	v_sub_f32_e32 v86, v86, v170
	v_sub_f32_e32 v87, v87, v170
	v_sub_f32_e32 v88, v88, v170
	v_sub_f32_e32 v89, v89, v170
	v_sub_f32_e32 v90, v90, v170
	v_sub_f32_e32 v91, v91, v170
	v_sub_f32_e32 v92, v92, v170
	v_sub_f32_e32 v93, v93, v170
	v_sub_f32_e32 v94, v94, v170
	v_sub_f32_e32 v95, v95, v170
	s_mov_b32 s9, 1
.Lagqa_nors_2:
	s_waitcnt lgkmcnt(3)
	v_mfma_f32_32x32x16_bf16 v[32:47], v[136:139], v[112:115], v[218:233]
	v_exp_f32_e32 v64, v64
	v_exp_f32_e32 v80, v80
	v_exp_f32_e32 v65, v65
	ds_read_b128 v[136:139], v243 offset:64
	ds_read_b64_tr_b16 v[192:193], v163 offset:3072
	ds_read_b64_tr_b16 v[194:195], v163 offset:4608
	v_mfma_f32_32x32x16_bf16 v[0:15], v[184:187], v[104:107], v[0:15]
	v_exp_f32_e32 v81, v81
	v_exp_f32_e32 v66, v66
	ds_read_b64_tr_b16 v[196:197], v163 offset:3136
	ds_read_b64_tr_b16 v[198:199], v163 offset:4672
	s_waitcnt lgkmcnt(7)
	v_mfma_f32_32x32x16_bf16 v[48:63], v[140:143], v[112:115], v[218:233]
	v_exp_f32_e32 v82, v82
	v_cvt_pk_bf16_f32 v96, v64, v65
	v_exp_f32_e32 v67, v67
	ds_read_b128 v[140:143], v243 offset:4672
	ds_read_b64_tr_b16 v[200:201], v163 offset:9216
	ds_read_b64_tr_b16 v[202:203], v163 offset:10752
	v_mfma_f32_32x32x16_bf16 v[16:31], v[188:191], v[104:107], v[16:31]
	v_exp_f32_e32 v83, v83
	v_exp_f32_e32 v68, v68
	v_exp_f32_e32 v84, v84
	ds_read_b64_tr_b16 v[204:205], v163 offset:9280
	ds_read_b64_tr_b16 v[206:207], v163 offset:10816
	s_waitcnt lgkmcnt(11)
	v_mfma_f32_32x32x16_bf16 v[32:47], v[144:147], v[116:119], v[32:47]
	v_cvt_pk_bf16_f32 v97, v66, v67
	v_exp_f32_e32 v69, v69
	v_exp_f32_e32 v85, v85
	ds_read_b128 v[144:147], v243 offset:96
	v_mfma_f32_16x16x32_bf16 v[234:237], v[246:249], v[104:107], v[234:237]
	v_cvt_pk_bf16_f32 v104, v80, v81
	v_cvt_pk_bf16_f32 v105, v82, v83
	v_exp_f32_e32 v70, v70
	v_exp_f32_e32 v86, v86
	s_waitcnt lgkmcnt(11)
	v_mfma_f32_32x32x16_bf16 v[48:63], v[148:151], v[116:119], v[48:63]
	v_cvt_pk_bf16_f32 v98, v68, v69
	v_cvt_pk_bf16_f32 v106, v84, v85
	v_exp_f32_e32 v71, v71
	v_exp_f32_e32 v87, v87
	ds_read_b128 v[148:151], v243 offset:4704
	s_waitcnt lgkmcnt(9)
	v_mfma_f32_32x32x16_bf16 v[0:15], v[192:195], v[100:103], v[0:15]
	v_exp_f32_e32 v72, v72
	v_exp_f32_e32 v88, v88
	v_mfma_f32_32x32x16_bf16 v[32:47], v[136:139], v[120:123], v[32:47]
	v_cvt_pk_bf16_f32 v99, v70, v71
	v_cvt_pk_bf16_f32 v107, v86, v87
	v_exp_f32_e32 v73, v73
	s_waitcnt vmcnt(3)
	ds_write_b128 v238, v[208:211] offset:9216
	s_waitcnt vmcnt(2)
	ds_write_b128 v164, v[212:215]
	s_waitcnt lgkmcnt(9)
	v_mfma_f32_32x32x16_bf16 v[16:31], v[196:199], v[100:103], v[16:31]
	v_exp_f32_e32 v89, v89
	v_exp_f32_e32 v74, v74
	v_exp_f32_e32 v90, v90
	s_waitcnt lgkmcnt(8)
	v_mfma_f32_32x32x16_bf16 v[48:63], v[140:143], v[120:123], v[48:63]
	v_exp_f32_e32 v75, v75
	v_exp_f32_e32 v91, v91
	v_mfma_f32_16x16x32_bf16 v[234:237], v[246:249], v[100:103], v[234:237]
	v_cvt_pk_bf16_f32 v100, v72, v73
	v_exp_f32_e32 v76, v76
	v_exp_f32_e32 v92, v92
	v_cvt_pk_bf16_f32 v101, v74, v75
	ds_read_b64_tr_b16 v[176:177], v162 offset:0
	ds_read_b64_tr_b16 v[178:179], v162 offset:1536
	s_waitcnt lgkmcnt(5)
	v_mfma_f32_32x32x16_bf16 v[32:47], v[144:147], v[124:127], v[32:47]
	v_exp_f32_e32 v77, v77
	v_exp_f32_e32 v93, v93
	v_exp_f32_e32 v78, v78
	ds_read_b64_tr_b16 v[180:181], v162 offset:64
	ds_read_b64_tr_b16 v[182:183], v162 offset:1600
	v_mfma_f32_32x32x16_bf16 v[0:15], v[200:203], v[108:111], v[0:15]
	v_exp_f32_e32 v94, v94
	v_cvt_pk_bf16_f32 v102, v76, v77
	v_exp_f32_e32 v79, v79
	ds_read_b64_tr_b16 v[184:185], v162 offset:6144
	ds_read_b64_tr_b16 v[186:187], v162 offset:7680
	s_waitcnt lgkmcnt(8)
	v_mfma_f32_32x32x16_bf16 v[48:63], v[148:151], v[124:127], v[48:63]
	v_exp_f32_e32 v95, v95
	v_cvt_pk_bf16_f32 v103, v78, v79
	ds_read_b64_tr_b16 v[188:189], v162 offset:6208
	ds_read_b64_tr_b16 v[190:191], v162 offset:7744
	v_mfma_f32_32x32x16_bf16 v[16:31], v[204:207], v[108:111], v[16:31]
	v_mfma_f32_16x16x32_bf16 v[234:237], v[246:249], v[108:111], v[234:237]
	v_cvt_pk_bf16_f32 v108, v88, v89
	v_cvt_pk_bf16_f32 v109, v90, v91
	v_cvt_pk_bf16_f32 v110, v92, v93
	v_cvt_pk_bf16_f32 v111, v94, v95
	s_cmp_lg_u32 s9, 0
	s_cbranch_scc0 .Lagqa_noresc_3
; #define AT_STEP(SC0, SC1, SN0, SN1, t, DOK, DOV) do { \
;             if (DOK) AT_GLOADK(((t) + 2) * 64); \
;             if (DOV) { AT_GLOADV(((t) + 1) * 64); AT_QK(SN0, SN1, ((t) + 1) & 1); } \
;             AT_SMPV(SC0, SC1, (t) & 1); \
;             if (DOK) AT_WRITEK((t) & 1); \
;             if (DOV) AT_WRITEV(((t) + 1) & 1); \
;             __syncthreads(); } while (0)
; template <bool MLA>
; DI void attn_phase(const int TID, const int BID, LAS unsigned char* lds, const Params& p, bool need_ctx) {
;     ...
;         for (; t < ntile - 2; t += 2) {
;             AT_STEP(sa0, sa1, sb0, sb1, t, true, true);
;             AT_STEP(sb0, sb1, sa0, sa1, t + 1, true, true);
	s_nop 15
	v_mul_f32_e32 v0, v0, v166
	v_mul_f32_e32 v1, v1, v166
	v_mul_f32_e32 v2, v2, v166
	v_mul_f32_e32 v3, v3, v166
	v_mul_f32_e32 v4, v4, v166
	v_mul_f32_e32 v5, v5, v166
	v_mul_f32_e32 v6, v6, v166
	v_mul_f32_e32 v7, v7, v166
	v_mul_f32_e32 v8, v8, v166
	v_mul_f32_e32 v9, v9, v166
	v_mul_f32_e32 v10, v10, v166
	v_mul_f32_e32 v11, v11, v166
	v_mul_f32_e32 v12, v12, v166
	v_mul_f32_e32 v13, v13, v166
	v_mul_f32_e32 v14, v14, v166
	v_mul_f32_e32 v15, v15, v166
	v_mul_f32_e32 v16, v16, v166
	v_mul_f32_e32 v17, v17, v166
	v_mul_f32_e32 v18, v18, v166
	v_mul_f32_e32 v19, v19, v166
	v_mul_f32_e32 v20, v20, v166
	v_mul_f32_e32 v21, v21, v166
	v_mul_f32_e32 v22, v22, v166
	v_mul_f32_e32 v23, v23, v166
	v_mul_f32_e32 v24, v24, v166
	v_mul_f32_e32 v25, v25, v166
	v_mul_f32_e32 v26, v26, v166
	v_mul_f32_e32 v27, v27, v166
	v_mul_f32_e32 v28, v28, v166
	v_mul_f32_e32 v29, v29, v166
	v_mul_f32_e32 v30, v30, v166
	v_mul_f32_e32 v31, v31, v166
	v_add_u32_e32 v170, 64, v175
	ds_bpermute_b32 v173, v170, v166
	v_mul_f32_e32 v234, v234, v166
	s_waitcnt lgkmcnt(0)
	v_mul_f32_e32 v235, v235, v173
.Lagqa_noresc_3:
	s_nop 1
	s_waitcnt lgkmcnt(8)
	s_barrier
	ds_read_b128 v[136:139], v243 offset:9216
	ds_read_b128 v[140:143], v243 offset:13824
	ds_read_b128 v[144:147], v243 offset:9248
	ds_read_b128 v[148:151], v243 offset:13856
	s_waitcnt lgkmcnt(10)
	v_mfma_f32_32x32x16_bf16 v[0:15], v[176:179], v[96:99], v[0:15]
	v_max3_f32 v168, v32, v33, v34
	v_max3_f32 v170, v48, v49, v50
	v_max3_f32 v168, v168, v35, v36
	v_max3_f32 v170, v170, v51, v52
	v_max3_f32 v168, v168, v37, v38
	s_mov_b32 s55, s52
	s_mov_b32 s52, s53
	s_mov_b32 s53, s54
	s_mov_b32 s54, s55
	s_mov_b32 s9, 0
	s_waitcnt lgkmcnt(8)
	v_mfma_f32_32x32x16_bf16 v[16:31], v[180:183], v[96:99], v[16:31]
	v_max3_f32 v170, v170, v53, v54
	v_max3_f32 v168, v168, v39, v40
	v_max3_f32 v170, v170, v55, v56
	v_max3_f32 v168, v168, v41, v42
	v_max3_f32 v170, v170, v57, v58
	global_load_dwordx4 v[208:211], v167, s[2:3]
	global_load_dwordx4 v[212:215], v167, s[4:5]
	s_add_u32 s2, s2, 0x2000
	s_addc_u32 s3, s3, 0
	s_add_u32 s4, s4, 0x2000
	s_addc_u32 s5, s5, 0
	v_add_u32_e32 v163, s53, v240
	v_add_u32_e32 v164, s54, v241
	v_mfma_f32_16x16x32_bf16 v[234:237], v[246:249], v[96:99], v[234:237]
	v_max3_f32 v168, v168, v43, v44
	v_max3_f32 v170, v170, v59, v60
	v_max3_f32 v168, v168, v45, v46
	v_max3_f32 v170, v170, v61, v62
	v_max3_f32 v168, v168, v170, v47
	v_max_f32_e32 v168, v168, v63
	v_cmp_lt_f32_e32 vcc, 0x41000000, v168
	s_cbranch_vccz .Lagqa_nors_4
	v_mov_b32_e32 v170, v168
	s_nop 1
	v_permlane32_swap_b32_e32 v168, v170
	v_max_f32_e32 v168, v168, v170
	v_max_f32_e32 v170, 0, v168
	v_exp_f32_e64 v166, -v170
	v_sub_f32_e32 v218, v218, v170
	v_sub_f32_e32 v219, v219, v170
	v_sub_f32_e32 v220, v220, v170
	v_sub_f32_e32 v221, v221, v170
	v_sub_f32_e32 v222, v222, v170
	v_sub_f32_e32 v223, v223, v170
	v_sub_f32_e32 v224, v224, v170
	v_sub_f32_e32 v225, v225, v170
	v_sub_f32_e32 v226, v226, v170
	v_sub_f32_e32 v227, v227, v170
	v_sub_f32_e32 v228, v228, v170
	v_sub_f32_e32 v229, v229, v170
	v_sub_f32_e32 v230, v230, v170
	v_sub_f32_e32 v231, v231, v170
	v_sub_f32_e32 v232, v232, v170
	v_sub_f32_e32 v233, v233, v170
	v_sub_f32_e32 v32, v32, v170
	v_sub_f32_e32 v33, v33, v170
	v_sub_f32_e32 v34, v34, v170
	v_sub_f32_e32 v35, v35, v170
	v_sub_f32_e32 v36, v36, v170
	v_sub_f32_e32 v37, v37, v170
	v_sub_f32_e32 v38, v38, v170
	v_sub_f32_e32 v39, v39, v170
	v_sub_f32_e32 v40, v40, v170
	v_sub_f32_e32 v41, v41, v170
	v_sub_f32_e32 v42, v42, v170
	v_sub_f32_e32 v43, v43, v170
	v_sub_f32_e32 v44, v44, v170
	v_sub_f32_e32 v45, v45, v170
	v_sub_f32_e32 v46, v46, v170
	v_sub_f32_e32 v47, v47, v170
	v_sub_f32_e32 v48, v48, v170
	v_sub_f32_e32 v49, v49, v170
	v_sub_f32_e32 v50, v50, v170
	v_sub_f32_e32 v51, v51, v170
	v_sub_f32_e32 v52, v52, v170
	v_sub_f32_e32 v53, v53, v170
	v_sub_f32_e32 v54, v54, v170
	v_sub_f32_e32 v55, v55, v170
	v_sub_f32_e32 v56, v56, v170
	v_sub_f32_e32 v57, v57, v170
	v_sub_f32_e32 v58, v58, v170
	v_sub_f32_e32 v59, v59, v170
	v_sub_f32_e32 v60, v60, v170
	v_sub_f32_e32 v61, v61, v170
	v_sub_f32_e32 v62, v62, v170
	v_sub_f32_e32 v63, v63, v170
	s_mov_b32 s9, 1
.Lagqa_nors_4:
	s_waitcnt lgkmcnt(3)
	v_mfma_f32_32x32x16_bf16 v[64:79], v[136:139], v[112:115], v[218:233]
	v_exp_f32_e32 v32, v32
	v_exp_f32_e32 v48, v48
	v_exp_f32_e32 v33, v33
	ds_read_b128 v[136:139], v243 offset:9280
	ds_read_b64_tr_b16 v[192:193], v162 offset:3072
	ds_read_b64_tr_b16 v[194:195], v162 offset:4608
	v_mfma_f32_32x32x16_bf16 v[0:15], v[184:187], v[104:107], v[0:15]
	v_exp_f32_e32 v49, v49
	v_exp_f32_e32 v34, v34
	ds_read_b64_tr_b16 v[196:197], v162 offset:3136
	ds_read_b64_tr_b16 v[198:199], v162 offset:4672
	s_waitcnt lgkmcnt(7)
	v_mfma_f32_32x32x16_bf16 v[80:95], v[140:143], v[112:115], v[218:233]
	v_exp_f32_e32 v50, v50
	v_cvt_pk_bf16_f32 v96, v32, v33
	v_exp_f32_e32 v35, v35
	ds_read_b128 v[140:143], v243 offset:13888
	ds_read_b64_tr_b16 v[200:201], v162 offset:9216
	ds_read_b64_tr_b16 v[202:203], v162 offset:10752
	v_mfma_f32_32x32x16_bf16 v[16:31], v[188:191], v[104:107], v[16:31]
	v_exp_f32_e32 v51, v51
	v_exp_f32_e32 v36, v36
	v_exp_f32_e32 v52, v52
	ds_read_b64_tr_b16 v[204:205], v162 offset:9280
	ds_read_b64_tr_b16 v[206:207], v162 offset:10816
	s_waitcnt lgkmcnt(11)
	v_mfma_f32_32x32x16_bf16 v[64:79], v[144:147], v[116:119], v[64:79]
	v_cvt_pk_bf16_f32 v97, v34, v35
	v_exp_f32_e32 v37, v37
	v_exp_f32_e32 v53, v53
	ds_read_b128 v[144:147], v243 offset:9312
	v_mfma_f32_16x16x32_bf16 v[234:237], v[246:249], v[104:107], v[234:237]
	v_cvt_pk_bf16_f32 v104, v48, v49
	v_cvt_pk_bf16_f32 v105, v50, v51
	v_exp_f32_e32 v38, v38
	v_exp_f32_e32 v54, v54
	s_waitcnt lgkmcnt(11)
; #define AT_STEP(SC0, SC1, SN0, SN1, t, DOK, DOV) do { \
;             if (DOK) AT_GLOADK(((t) + 2) * 64); \
;             if (DOV) { AT_GLOADV(((t) + 1) * 64); AT_QK(SN0, SN1, ((t) + 1) & 1); } \
;             AT_SMPV(SC0, SC1, (t) & 1); \
;             if (DOK) AT_WRITEK((t) & 1); \
;             if (DOV) AT_WRITEV(((t) + 1) & 1); \
;             __syncthreads(); } while (0)
; template <bool MLA>
; DI void attn_phase(const int TID, const int BID, LAS unsigned char* lds, const Params& p, bool need_ctx) {
;     ...
;         for (; t < ntile - 2; t += 2) {
;             AT_STEP(sa0, sa1, sb0, sb1, t, true, true);
;             AT_STEP(sb0, sb1, sa0, sa1, t + 1, true, true);
;         }
;         AT_STEP(sa0, sa1, sb0, sb1, t, false, true);
;         AT_STEP(sb0, sb1, sa0, sa1, t + 1, false, false);
	v_mfma_f32_32x32x16_bf16 v[80:95], v[148:151], v[116:119], v[80:95]
	v_cvt_pk_bf16_f32 v98, v36, v37
	v_cvt_pk_bf16_f32 v106, v52, v53
	v_exp_f32_e32 v39, v39
	v_exp_f32_e32 v55, v55
	ds_read_b128 v[148:151], v243 offset:13920
	s_waitcnt lgkmcnt(9)
	v_mfma_f32_32x32x16_bf16 v[0:15], v[192:195], v[100:103], v[0:15]
	v_exp_f32_e32 v40, v40
	v_exp_f32_e32 v56, v56
	v_mfma_f32_32x32x16_bf16 v[64:79], v[136:139], v[120:123], v[64:79]
	v_cvt_pk_bf16_f32 v99, v38, v39
	v_cvt_pk_bf16_f32 v107, v54, v55
	v_exp_f32_e32 v41, v41
	s_waitcnt vmcnt(3)
	ds_write_b128 v238, v[152:155]
	s_waitcnt vmcnt(2)
	ds_write_b128 v164, v[156:159]
	s_waitcnt lgkmcnt(9)
	v_mfma_f32_32x32x16_bf16 v[16:31], v[196:199], v[100:103], v[16:31]
	v_exp_f32_e32 v57, v57
	v_exp_f32_e32 v42, v42
	v_exp_f32_e32 v58, v58
	s_waitcnt lgkmcnt(8)
	v_mfma_f32_32x32x16_bf16 v[80:95], v[140:143], v[120:123], v[80:95]
	v_exp_f32_e32 v43, v43
	v_exp_f32_e32 v59, v59
	v_mfma_f32_16x16x32_bf16 v[234:237], v[246:249], v[100:103], v[234:237]
	v_cvt_pk_bf16_f32 v100, v40, v41
	v_exp_f32_e32 v44, v44
	v_exp_f32_e32 v60, v60
	v_cvt_pk_bf16_f32 v101, v42, v43
	ds_read_b64_tr_b16 v[176:177], v163 offset:0
	ds_read_b64_tr_b16 v[178:179], v163 offset:1536
	s_waitcnt lgkmcnt(5)
	v_mfma_f32_32x32x16_bf16 v[64:79], v[144:147], v[124:127], v[64:79]
	v_exp_f32_e32 v45, v45
	v_exp_f32_e32 v61, v61
	v_exp_f32_e32 v46, v46
	ds_read_b64_tr_b16 v[180:181], v163 offset:64
	ds_read_b64_tr_b16 v[182:183], v163 offset:1600
	v_mfma_f32_32x32x16_bf16 v[0:15], v[200:203], v[108:111], v[0:15]
	v_exp_f32_e32 v62, v62
	v_cvt_pk_bf16_f32 v102, v44, v45
	v_exp_f32_e32 v47, v47
	ds_read_b64_tr_b16 v[184:185], v163 offset:6144
	ds_read_b64_tr_b16 v[186:187], v163 offset:7680
	s_waitcnt lgkmcnt(8)
	v_mfma_f32_32x32x16_bf16 v[80:95], v[148:151], v[124:127], v[80:95]
	v_exp_f32_e32 v63, v63
	v_cvt_pk_bf16_f32 v103, v46, v47
	ds_read_b64_tr_b16 v[188:189], v163 offset:6208
	ds_read_b64_tr_b16 v[190:191], v163 offset:7744
	v_mfma_f32_32x32x16_bf16 v[16:31], v[204:207], v[108:111], v[16:31]
	v_mfma_f32_16x16x32_bf16 v[234:237], v[246:249], v[108:111], v[234:237]
	v_cvt_pk_bf16_f32 v108, v56, v57
	v_cvt_pk_bf16_f32 v109, v58, v59
	v_cvt_pk_bf16_f32 v110, v60, v61
	v_cvt_pk_bf16_f32 v111, v62, v63
	s_cmp_lg_u32 s9, 0
	s_cbranch_scc0 .Lagqa_noresc_5
	s_nop 15
	v_mul_f32_e32 v0, v0, v166
	v_mul_f32_e32 v1, v1, v166
	v_mul_f32_e32 v2, v2, v166
	v_mul_f32_e32 v3, v3, v166
	v_mul_f32_e32 v4, v4, v166
	v_mul_f32_e32 v5, v5, v166
	v_mul_f32_e32 v6, v6, v166
	v_mul_f32_e32 v7, v7, v166
	v_mul_f32_e32 v8, v8, v166
	v_mul_f32_e32 v9, v9, v166
	v_mul_f32_e32 v10, v10, v166
	v_mul_f32_e32 v11, v11, v166
	v_mul_f32_e32 v12, v12, v166
	v_mul_f32_e32 v13, v13, v166
	v_mul_f32_e32 v14, v14, v166
	v_mul_f32_e32 v15, v15, v166
	v_mul_f32_e32 v16, v16, v166
	v_mul_f32_e32 v17, v17, v166
	v_mul_f32_e32 v18, v18, v166
	v_mul_f32_e32 v19, v19, v166
	v_mul_f32_e32 v20, v20, v166
	v_mul_f32_e32 v21, v21, v166
	v_mul_f32_e32 v22, v22, v166
	v_mul_f32_e32 v23, v23, v166
	v_mul_f32_e32 v24, v24, v166
	v_mul_f32_e32 v25, v25, v166
	v_mul_f32_e32 v26, v26, v166
	v_mul_f32_e32 v27, v27, v166
	v_mul_f32_e32 v28, v28, v166
	v_mul_f32_e32 v29, v29, v166
	v_mul_f32_e32 v30, v30, v166
	v_mul_f32_e32 v31, v31, v166
	v_add_u32_e32 v170, 64, v175
	ds_bpermute_b32 v173, v170, v166
	v_mul_f32_e32 v234, v234, v166
	s_waitcnt lgkmcnt(0)
	v_mul_f32_e32 v235, v235, v173
.Lagqa_noresc_5:
	s_nop 1
	s_waitcnt lgkmcnt(8)
	s_barrier
	s_add_i32 s7, s7, -1
	s_cmp_lg_u32 s7, 0
	s_cbranch_scc1 .Lagqa_loop
.Lagqa_tail:
	ds_read_b128 v[136:139], v243 offset:0
	ds_read_b128 v[140:143], v243 offset:4608
	ds_read_b128 v[144:147], v243 offset:32
	ds_read_b128 v[148:151], v243 offset:4640
	s_waitcnt lgkmcnt(10)
	v_mfma_f32_32x32x16_bf16 v[0:15], v[176:179], v[96:99], v[0:15]
	v_max3_f32 v168, v64, v65, v66
	v_max3_f32 v170, v80, v81, v82
	v_max3_f32 v168, v168, v67, v68
	v_max3_f32 v170, v170, v83, v84
	v_max3_f32 v168, v168, v69, v70
	s_mov_b32 s55, s52
	s_mov_b32 s52, s53
	s_mov_b32 s53, s54
	s_mov_b32 s54, s55
	s_mov_b32 s9, 0
	s_waitcnt lgkmcnt(8)
	v_mfma_f32_32x32x16_bf16 v[16:31], v[180:183], v[96:99], v[16:31]
	v_max3_f32 v170, v170, v85, v86
	v_max3_f32 v168, v168, v71, v72
	v_max3_f32 v170, v170, v87, v88
	v_max3_f32 v168, v168, v73, v74
	v_max3_f32 v170, v170, v89, v90
	global_load_dwordx4 v[156:159], v167, s[4:5]
	s_add_u32 s4, s4, 0x2000
	s_addc_u32 s5, s5, 0
	v_add_u32_e32 v162, s53, v240
	v_add_u32_e32 v164, s54, v241
	v_mfma_f32_16x16x32_bf16 v[234:237], v[246:249], v[96:99], v[234:237]
	v_max3_f32 v168, v168, v75, v76
	v_max3_f32 v170, v170, v91, v92
	v_max3_f32 v168, v168, v77, v78
	v_max3_f32 v170, v170, v93, v94
	v_max3_f32 v168, v168, v170, v79
	v_max_f32_e32 v168, v168, v95
	v_cmp_lt_f32_e32 vcc, 0x41000000, v168
	s_cbranch_vccz .Lagqa_nors_6
	v_mov_b32_e32 v170, v168
	s_nop 1
	v_permlane32_swap_b32_e32 v168, v170
	v_max_f32_e32 v168, v168, v170
	v_max_f32_e32 v170, 0, v168
	v_exp_f32_e64 v166, -v170
	v_sub_f32_e32 v218, v218, v170
	v_sub_f32_e32 v219, v219, v170
	v_sub_f32_e32 v220, v220, v170
	v_sub_f32_e32 v221, v221, v170
	v_sub_f32_e32 v222, v222, v170
	v_sub_f32_e32 v223, v223, v170
	v_sub_f32_e32 v224, v224, v170
	v_sub_f32_e32 v225, v225, v170
	v_sub_f32_e32 v226, v226, v170
	v_sub_f32_e32 v227, v227, v170
	v_sub_f32_e32 v228, v228, v170
	v_sub_f32_e32 v229, v229, v170
	v_sub_f32_e32 v230, v230, v170
	v_sub_f32_e32 v231, v231, v170
	v_sub_f32_e32 v232, v232, v170
	v_sub_f32_e32 v233, v233, v170
	v_sub_f32_e32 v64, v64, v170
	v_sub_f32_e32 v65, v65, v170
	v_sub_f32_e32 v66, v66, v170
	v_sub_f32_e32 v67, v67, v170
	v_sub_f32_e32 v68, v68, v170
	v_sub_f32_e32 v69, v69, v170
	v_sub_f32_e32 v70, v70, v170
	v_sub_f32_e32 v71, v71, v170
	v_sub_f32_e32 v72, v72, v170
	v_sub_f32_e32 v73, v73, v170
	v_sub_f32_e32 v74, v74, v170
	v_sub_f32_e32 v75, v75, v170
	v_sub_f32_e32 v76, v76, v170
	v_sub_f32_e32 v77, v77, v170
	v_sub_f32_e32 v78, v78, v170
	v_sub_f32_e32 v79, v79, v170
	v_sub_f32_e32 v80, v80, v170
	v_sub_f32_e32 v81, v81, v170
	v_sub_f32_e32 v82, v82, v170
	v_sub_f32_e32 v83, v83, v170
	v_sub_f32_e32 v84, v84, v170
	v_sub_f32_e32 v85, v85, v170
	v_sub_f32_e32 v86, v86, v170
	v_sub_f32_e32 v87, v87, v170
	v_sub_f32_e32 v88, v88, v170
	v_sub_f32_e32 v89, v89, v170
	v_sub_f32_e32 v90, v90, v170
	v_sub_f32_e32 v91, v91, v170
	v_sub_f32_e32 v92, v92, v170
	v_sub_f32_e32 v93, v93, v170
	v_sub_f32_e32 v94, v94, v170
	v_sub_f32_e32 v95, v95, v170
	s_mov_b32 s9, 1
; #define AT_STEP(SC0, SC1, SN0, SN1, t, DOK, DOV) do { \
;             if (DOK) AT_GLOADK(((t) + 2) * 64); \
;             if (DOV) { AT_GLOADV(((t) + 1) * 64); AT_QK(SN0, SN1, ((t) + 1) & 1); } \
;             AT_SMPV(SC0, SC1, (t) & 1); \
;             if (DOK) AT_WRITEK((t) & 1); \
;             if (DOV) AT_WRITEV(((t) + 1) & 1); \
;             __syncthreads(); } while (0)
; template <bool MLA>
; DI void attn_phase(const int TID, const int BID, LAS unsigned char* lds, const Params& p, bool need_ctx) {
;     ...
;         AT_STEP(sa0, sa1, sb0, sb1, t, false, true);
;         AT_STEP(sb0, sb1, sa0, sa1, t + 1, false, false);
.Lagqa_nors_6:
	s_waitcnt lgkmcnt(3)
	v_mfma_f32_32x32x16_bf16 v[32:47], v[136:139], v[112:115], v[218:233]
	v_exp_f32_e32 v64, v64
	v_exp_f32_e32 v80, v80
	v_exp_f32_e32 v65, v65
	ds_read_b128 v[136:139], v243 offset:64
	ds_read_b64_tr_b16 v[192:193], v163 offset:3072
	ds_read_b64_tr_b16 v[194:195], v163 offset:4608
	v_mfma_f32_32x32x16_bf16 v[0:15], v[184:187], v[104:107], v[0:15]
	v_exp_f32_e32 v81, v81
	v_exp_f32_e32 v66, v66
	ds_read_b64_tr_b16 v[196:197], v163 offset:3136
	ds_read_b64_tr_b16 v[198:199], v163 offset:4672
	s_waitcnt lgkmcnt(7)
	v_mfma_f32_32x32x16_bf16 v[48:63], v[140:143], v[112:115], v[218:233]
	v_exp_f32_e32 v82, v82
	v_cvt_pk_bf16_f32 v96, v64, v65
	v_exp_f32_e32 v67, v67
	ds_read_b128 v[140:143], v243 offset:4672
	ds_read_b64_tr_b16 v[200:201], v163 offset:9216
	ds_read_b64_tr_b16 v[202:203], v163 offset:10752
	v_mfma_f32_32x32x16_bf16 v[16:31], v[188:191], v[104:107], v[16:31]
	v_exp_f32_e32 v83, v83
	v_exp_f32_e32 v68, v68
	v_exp_f32_e32 v84, v84
	ds_read_b64_tr_b16 v[204:205], v163 offset:9280
	ds_read_b64_tr_b16 v[206:207], v163 offset:10816
	s_waitcnt lgkmcnt(11)
	v_mfma_f32_32x32x16_bf16 v[32:47], v[144:147], v[116:119], v[32:47]
	v_cvt_pk_bf16_f32 v97, v66, v67
	v_exp_f32_e32 v69, v69
	v_exp_f32_e32 v85, v85
	ds_read_b128 v[144:147], v243 offset:96
	v_mfma_f32_16x16x32_bf16 v[234:237], v[246:249], v[104:107], v[234:237]
	v_cvt_pk_bf16_f32 v104, v80, v81
	v_cvt_pk_bf16_f32 v105, v82, v83
	v_exp_f32_e32 v70, v70
	v_exp_f32_e32 v86, v86
	s_waitcnt lgkmcnt(11)
	v_mfma_f32_32x32x16_bf16 v[48:63], v[148:151], v[116:119], v[48:63]
	v_cvt_pk_bf16_f32 v98, v68, v69
	v_cvt_pk_bf16_f32 v106, v84, v85
	v_exp_f32_e32 v71, v71
	v_exp_f32_e32 v87, v87
	ds_read_b128 v[148:151], v243 offset:4704
	s_waitcnt lgkmcnt(9)
	v_mfma_f32_32x32x16_bf16 v[0:15], v[192:195], v[100:103], v[0:15]
	v_exp_f32_e32 v72, v72
	v_exp_f32_e32 v88, v88
	v_mfma_f32_32x32x16_bf16 v[32:47], v[136:139], v[120:123], v[32:47]
	v_cvt_pk_bf16_f32 v99, v70, v71
	v_cvt_pk_bf16_f32 v107, v86, v87
	v_exp_f32_e32 v73, v73
	s_waitcnt vmcnt(2)
	ds_write_b128 v238, v[208:211] offset:9216
	s_waitcnt vmcnt(1)
	ds_write_b128 v164, v[212:215]
	s_waitcnt lgkmcnt(9)
	v_mfma_f32_32x32x16_bf16 v[16:31], v[196:199], v[100:103], v[16:31]
	v_exp_f32_e32 v89, v89
	v_exp_f32_e32 v74, v74
	v_exp_f32_e32 v90, v90
	s_waitcnt lgkmcnt(8)
	v_mfma_f32_32x32x16_bf16 v[48:63], v[140:143], v[120:123], v[48:63]
	v_exp_f32_e32 v75, v75
	v_exp_f32_e32 v91, v91
	v_mfma_f32_16x16x32_bf16 v[234:237], v[246:249], v[100:103], v[234:237]
	v_cvt_pk_bf16_f32 v100, v72, v73
	v_exp_f32_e32 v76, v76
	v_exp_f32_e32 v92, v92
	v_cvt_pk_bf16_f32 v101, v74, v75
	ds_read_b64_tr_b16 v[176:177], v162 offset:0
	ds_read_b64_tr_b16 v[178:179], v162 offset:1536
	s_waitcnt lgkmcnt(5)
	v_mfma_f32_32x32x16_bf16 v[32:47], v[144:147], v[124:127], v[32:47]
	v_exp_f32_e32 v77, v77
	v_exp_f32_e32 v93, v93
	v_exp_f32_e32 v78, v78
	ds_read_b64_tr_b16 v[180:181], v162 offset:64
	ds_read_b64_tr_b16 v[182:183], v162 offset:1600
	v_mfma_f32_32x32x16_bf16 v[0:15], v[200:203], v[108:111], v[0:15]
	v_exp_f32_e32 v94, v94
	v_cvt_pk_bf16_f32 v102, v76, v77
	v_exp_f32_e32 v79, v79
	ds_read_b64_tr_b16 v[184:185], v162 offset:6144
	ds_read_b64_tr_b16 v[186:187], v162 offset:7680
	s_waitcnt lgkmcnt(8)
	v_mfma_f32_32x32x16_bf16 v[48:63], v[148:151], v[124:127], v[48:63]
	v_exp_f32_e32 v95, v95
	v_cvt_pk_bf16_f32 v103, v78, v79
	ds_read_b64_tr_b16 v[188:189], v162 offset:6208
	ds_read_b64_tr_b16 v[190:191], v162 offset:7744
	v_mfma_f32_32x32x16_bf16 v[16:31], v[204:207], v[108:111], v[16:31]
	v_mfma_f32_16x16x32_bf16 v[234:237], v[246:249], v[108:111], v[234:237]
	v_cvt_pk_bf16_f32 v108, v88, v89
	v_cvt_pk_bf16_f32 v109, v90, v91
	v_cvt_pk_bf16_f32 v110, v92, v93
	v_cvt_pk_bf16_f32 v111, v94, v95
	s_cmp_lg_u32 s9, 0
	s_cbranch_scc0 .Lagqa_noresc_7
	s_nop 15
	v_mul_f32_e32 v0, v0, v166
	v_mul_f32_e32 v1, v1, v166
	v_mul_f32_e32 v2, v2, v166
	v_mul_f32_e32 v3, v3, v166
	v_mul_f32_e32 v4, v4, v166
	v_mul_f32_e32 v5, v5, v166
	v_mul_f32_e32 v6, v6, v166
	v_mul_f32_e32 v7, v7, v166
	v_mul_f32_e32 v8, v8, v166
	v_mul_f32_e32 v9, v9, v166
	v_mul_f32_e32 v10, v10, v166
	v_mul_f32_e32 v11, v11, v166
	v_mul_f32_e32 v12, v12, v166
	v_mul_f32_e32 v13, v13, v166
	v_mul_f32_e32 v14, v14, v166
	v_mul_f32_e32 v15, v15, v166
	v_mul_f32_e32 v16, v16, v166
	v_mul_f32_e32 v17, v17, v166
	v_mul_f32_e32 v18, v18, v166
	v_mul_f32_e32 v19, v19, v166
	v_mul_f32_e32 v20, v20, v166
	v_mul_f32_e32 v21, v21, v166
	v_mul_f32_e32 v22, v22, v166
	v_mul_f32_e32 v23, v23, v166
	v_mul_f32_e32 v24, v24, v166
	v_mul_f32_e32 v25, v25, v166
	v_mul_f32_e32 v26, v26, v166
	v_mul_f32_e32 v27, v27, v166
	v_mul_f32_e32 v28, v28, v166
	v_mul_f32_e32 v29, v29, v166
	v_mul_f32_e32 v30, v30, v166
	v_mul_f32_e32 v31, v31, v166
	v_add_u32_e32 v170, 64, v175
	ds_bpermute_b32 v173, v170, v166
	v_mul_f32_e32 v234, v234, v166
	s_waitcnt lgkmcnt(0)
	v_mul_f32_e32 v235, v235, v173
.Lagqa_noresc_7:
	s_nop 1
	s_waitcnt lgkmcnt(8)
	s_barrier
	ds_read_b128 v[136:139], v243 offset:9216
	ds_read_b128 v[140:143], v243 offset:13824
	ds_read_b128 v[144:147], v243 offset:9248
	ds_read_b128 v[148:151], v243 offset:13856
	s_waitcnt lgkmcnt(10)
	v_mfma_f32_32x32x16_bf16 v[0:15], v[176:179], v[96:99], v[0:15]
	v_max3_f32 v168, v32, v33, v34
	v_max3_f32 v170, v48, v49, v50
	v_max3_f32 v168, v168, v35, v36
	v_max3_f32 v170, v170, v51, v52
	v_max3_f32 v168, v168, v37, v38
	s_mov_b32 s55, s52
	s_mov_b32 s52, s53
	s_mov_b32 s53, s54
	s_mov_b32 s54, s55
	s_mov_b32 s9, 0
	s_waitcnt lgkmcnt(8)
	v_mfma_f32_32x32x16_bf16 v[16:31], v[180:183], v[96:99], v[16:31]
	v_max3_f32 v170, v170, v53, v54
	v_max3_f32 v168, v168, v39, v40
	v_max3_f32 v170, v170, v55, v56
	v_max3_f32 v168, v168, v41, v42
	v_max3_f32 v170, v170, v57, v58
	v_add_u32_e32 v163, s53, v240
	v_add_u32_e32 v164, s54, v241
	v_mfma_f32_16x16x32_bf16 v[234:237], v[246:249], v[96:99], v[234:237]
	v_max3_f32 v168, v168, v43, v44
	v_max3_f32 v170, v170, v59, v60
	v_max3_f32 v168, v168, v45, v46
	v_max3_f32 v170, v170, v61, v62
	v_max3_f32 v168, v168, v170, v47
	v_max_f32_e32 v168, v168, v63
	v_cmp_lt_f32_e32 vcc, 0x41000000, v168
	s_cbranch_vccz .Lagqa_nors_8
	v_mov_b32_e32 v170, v168
	s_nop 1
	v_permlane32_swap_b32_e32 v168, v170
	v_max_f32_e32 v168, v168, v170
	v_max_f32_e32 v170, 0, v168
	v_exp_f32_e64 v166, -v170
	v_sub_f32_e32 v218, v218, v170
	v_sub_f32_e32 v219, v219, v170
	v_sub_f32_e32 v220, v220, v170
	v_sub_f32_e32 v221, v221, v170
	v_sub_f32_e32 v222, v222, v170
	v_sub_f32_e32 v223, v223, v170
	v_sub_f32_e32 v224, v224, v170
	v_sub_f32_e32 v225, v225, v170
	v_sub_f32_e32 v226, v226, v170
	v_sub_f32_e32 v227, v227, v170
	v_sub_f32_e32 v228, v228, v170
	v_sub_f32_e32 v229, v229, v170
	v_sub_f32_e32 v230, v230, v170
	v_sub_f32_e32 v231, v231, v170
	v_sub_f32_e32 v232, v232, v170
	v_sub_f32_e32 v233, v233, v170
	v_sub_f32_e32 v32, v32, v170
	v_sub_f32_e32 v33, v33, v170
	v_sub_f32_e32 v34, v34, v170
	v_sub_f32_e32 v35, v35, v170
	v_sub_f32_e32 v36, v36, v170
	v_sub_f32_e32 v37, v37, v170
	v_sub_f32_e32 v38, v38, v170
	v_sub_f32_e32 v39, v39, v170
	v_sub_f32_e32 v40, v40, v170
	v_sub_f32_e32 v41, v41, v170
	v_sub_f32_e32 v42, v42, v170
	v_sub_f32_e32 v43, v43, v170
	v_sub_f32_e32 v44, v44, v170
	v_sub_f32_e32 v45, v45, v170
	v_sub_f32_e32 v46, v46, v170
	v_sub_f32_e32 v47, v47, v170
	v_sub_f32_e32 v48, v48, v170
	v_sub_f32_e32 v49, v49, v170
	v_sub_f32_e32 v50, v50, v170
	v_sub_f32_e32 v51, v51, v170
	v_sub_f32_e32 v52, v52, v170
	v_sub_f32_e32 v53, v53, v170
	v_sub_f32_e32 v54, v54, v170
	v_sub_f32_e32 v55, v55, v170
	v_sub_f32_e32 v56, v56, v170
	v_sub_f32_e32 v57, v57, v170
	v_sub_f32_e32 v58, v58, v170
	v_sub_f32_e32 v59, v59, v170
	v_sub_f32_e32 v60, v60, v170
	v_sub_f32_e32 v61, v61, v170
	v_sub_f32_e32 v62, v62, v170
	v_sub_f32_e32 v63, v63, v170
	s_mov_b32 s9, 1
.Lagqa_nors_8:
	s_waitcnt lgkmcnt(3)
	v_mfma_f32_32x32x16_bf16 v[64:79], v[136:139], v[112:115], v[218:233]
	v_exp_f32_e32 v32, v32
	v_exp_f32_e32 v48, v48
	v_exp_f32_e32 v33, v33
	ds_read_b128 v[136:139], v243 offset:9280
	ds_read_b64_tr_b16 v[192:193], v162 offset:3072
	ds_read_b64_tr_b16 v[194:195], v162 offset:4608
	v_mfma_f32_32x32x16_bf16 v[0:15], v[184:187], v[104:107], v[0:15]
	v_exp_f32_e32 v49, v49
	v_exp_f32_e32 v34, v34
	ds_read_b64_tr_b16 v[196:197], v162 offset:3136
	ds_read_b64_tr_b16 v[198:199], v162 offset:4672
	s_waitcnt lgkmcnt(7)
	v_mfma_f32_32x32x16_bf16 v[80:95], v[140:143], v[112:115], v[218:233]
	v_exp_f32_e32 v50, v50
	v_cvt_pk_bf16_f32 v96, v32, v33
	v_exp_f32_e32 v35, v35
	ds_read_b128 v[140:143], v243 offset:13888
	ds_read_b64_tr_b16 v[200:201], v162 offset:9216
	ds_read_b64_tr_b16 v[202:203], v162 offset:10752
	v_mfma_f32_32x32x16_bf16 v[16:31], v[188:191], v[104:107], v[16:31]
	v_exp_f32_e32 v51, v51
	v_exp_f32_e32 v36, v36
	v_exp_f32_e32 v52, v52
	ds_read_b64_tr_b16 v[204:205], v162 offset:9280
	ds_read_b64_tr_b16 v[206:207], v162 offset:10816
	s_waitcnt lgkmcnt(11)
	v_mfma_f32_32x32x16_bf16 v[64:79], v[144:147], v[116:119], v[64:79]
	v_cvt_pk_bf16_f32 v97, v34, v35
	v_exp_f32_e32 v37, v37
	v_exp_f32_e32 v53, v53
	ds_read_b128 v[144:147], v243 offset:9312
	v_mfma_f32_16x16x32_bf16 v[234:237], v[246:249], v[104:107], v[234:237]
	v_cvt_pk_bf16_f32 v104, v48, v49
	v_cvt_pk_bf16_f32 v105, v50, v51
	v_exp_f32_e32 v38, v38
	v_exp_f32_e32 v54, v54
	s_waitcnt lgkmcnt(11)
	v_mfma_f32_32x32x16_bf16 v[80:95], v[148:151], v[116:119], v[80:95]
	v_cvt_pk_bf16_f32 v98, v36, v37
	v_cvt_pk_bf16_f32 v106, v52, v53
	v_exp_f32_e32 v39, v39
	v_exp_f32_e32 v55, v55
	ds_read_b128 v[148:151], v243 offset:13920
	s_waitcnt lgkmcnt(9)
	v_mfma_f32_32x32x16_bf16 v[0:15], v[192:195], v[100:103], v[0:15]
	v_exp_f32_e32 v40, v40
	v_exp_f32_e32 v56, v56
	v_mfma_f32_32x32x16_bf16 v[64:79], v[136:139], v[120:123], v[64:79]
	v_cvt_pk_bf16_f32 v99, v38, v39
	v_cvt_pk_bf16_f32 v107, v54, v55
	v_exp_f32_e32 v41, v41
	s_waitcnt vmcnt(0)
	ds_write_b128 v164, v[156:159]
	s_waitcnt lgkmcnt(8)
	v_mfma_f32_32x32x16_bf16 v[16:31], v[196:199], v[100:103], v[16:31]
	v_exp_f32_e32 v57, v57
	v_exp_f32_e32 v42, v42
	v_exp_f32_e32 v58, v58
	s_waitcnt lgkmcnt(7)
	v_mfma_f32_32x32x16_bf16 v[80:95], v[140:143], v[120:123], v[80:95]
	v_exp_f32_e32 v43, v43
	v_exp_f32_e32 v59, v59
	v_mfma_f32_16x16x32_bf16 v[234:237], v[246:249], v[100:103], v[234:237]
	v_cvt_pk_bf16_f32 v100, v40, v41
	v_exp_f32_e32 v44, v44
	v_exp_f32_e32 v60, v60
	v_cvt_pk_bf16_f32 v101, v42, v43
	ds_read_b64_tr_b16 v[176:177], v163 offset:0
	ds_read_b64_tr_b16 v[178:179], v163 offset:1536
	s_waitcnt lgkmcnt(4)
	v_mfma_f32_32x32x16_bf16 v[64:79], v[144:147], v[124:127], v[64:79]
	v_exp_f32_e32 v45, v45
	v_exp_f32_e32 v61, v61
	v_exp_f32_e32 v46, v46
	ds_read_b64_tr_b16 v[180:181], v163 offset:64
	ds_read_b64_tr_b16 v[182:183], v163 offset:1600
	v_mfma_f32_32x32x16_bf16 v[0:15], v[200:203], v[108:111], v[0:15]
	v_exp_f32_e32 v62, v62
	v_cvt_pk_bf16_f32 v102, v44, v45
	v_exp_f32_e32 v47, v47
	ds_read_b64_tr_b16 v[184:185], v163 offset:6144
	ds_read_b64_tr_b16 v[186:187], v163 offset:7680
	s_waitcnt lgkmcnt(7)
	v_mfma_f32_32x32x16_bf16 v[80:95], v[148:151], v[124:127], v[80:95]
	v_exp_f32_e32 v63, v63
	v_cvt_pk_bf16_f32 v103, v46, v47
	ds_read_b64_tr_b16 v[188:189], v163 offset:6208
	ds_read_b64_tr_b16 v[190:191], v163 offset:7744
	v_mfma_f32_32x32x16_bf16 v[16:31], v[204:207], v[108:111], v[16:31]
	v_mfma_f32_16x16x32_bf16 v[234:237], v[246:249], v[108:111], v[234:237]
	v_cvt_pk_bf16_f32 v108, v56, v57
	v_cvt_pk_bf16_f32 v109, v58, v59
	v_cvt_pk_bf16_f32 v110, v60, v61
	v_cvt_pk_bf16_f32 v111, v62, v63
	s_cmp_lg_u32 s9, 0
	s_cbranch_scc0 .Lagqa_noresc_9
	s_nop 15
	v_mul_f32_e32 v0, v0, v166
	v_mul_f32_e32 v1, v1, v166
	v_mul_f32_e32 v2, v2, v166
	v_mul_f32_e32 v3, v3, v166
	v_mul_f32_e32 v4, v4, v166
	v_mul_f32_e32 v5, v5, v166
	v_mul_f32_e32 v6, v6, v166
	v_mul_f32_e32 v7, v7, v166
	v_mul_f32_e32 v8, v8, v166
	v_mul_f32_e32 v9, v9, v166
	v_mul_f32_e32 v10, v10, v166
	v_mul_f32_e32 v11, v11, v166
	v_mul_f32_e32 v12, v12, v166
	v_mul_f32_e32 v13, v13, v166
	v_mul_f32_e32 v14, v14, v166
	v_mul_f32_e32 v15, v15, v166
	v_mul_f32_e32 v16, v16, v166
	v_mul_f32_e32 v17, v17, v166
	v_mul_f32_e32 v18, v18, v166
	v_mul_f32_e32 v19, v19, v166
	v_mul_f32_e32 v20, v20, v166
	v_mul_f32_e32 v21, v21, v166
	v_mul_f32_e32 v22, v22, v166
	v_mul_f32_e32 v23, v23, v166
	v_mul_f32_e32 v24, v24, v166
	v_mul_f32_e32 v25, v25, v166
	v_mul_f32_e32 v26, v26, v166
	v_mul_f32_e32 v27, v27, v166
	v_mul_f32_e32 v28, v28, v166
	v_mul_f32_e32 v29, v29, v166
	v_mul_f32_e32 v30, v30, v166
	v_mul_f32_e32 v31, v31, v166
	v_add_u32_e32 v170, 64, v175
	ds_bpermute_b32 v173, v170, v166
	v_mul_f32_e32 v234, v234, v166
	s_waitcnt lgkmcnt(0)
	v_mul_f32_e32 v235, v235, v173
.Lagqa_noresc_9:
	s_nop 1
	s_waitcnt lgkmcnt(8)
	s_barrier
	s_add_i32 s59, s6, s31
	s_cmp_ge_i32 s59, s8
	s_cbranch_scc1 .Lagqa_nonext
	s_cmpk_gt_i32 s59, 0x3ff
	s_cbranch_scc0 .Lagqa_mainitem_next
	s_add_i32 s21, s59, 0xfffffc00
	s_lshr_b32 s15, s21, 4
	s_and_b32 s18, s21, 15
	s_lshl_b32 s20, s15, 8
	s_add_i32 s20, s20, 0x4000
	s_mov_b32 s7, 0
	s_branch .Lagqa_decoded_next
